# speedup vs baseline: 1.0098x; 1.0098x over previous
; DI float lo16(unsigned w) { return __uint_as_float(w << 16); }
; DI float hi16(unsigned w) { return __uint_as_float(w & 0xffff0000u); }
; DI float rowscale(const float* ss, int row) {
;     const f32x4* p = (const f32x4*)(ss + (size_t)row * 16);
;     const f32x4 a = p[0], b = p[1], c = p[2], d = p[3];
;     const float s = (((a.x + a.y) + (a.z + a.w)) + ((b.x + b.y) + (b.z + b.w))) + (((c.x + c.y) + (c.z + c.w)) + ((d.x + d.y) + (d.z + d.w)));
;     return rsqrtf(s * (1.0f / 1024.0f) + EPS);
; }
; DI void rowscales8(const float* ss, int rowbase, int fr, int fq, float (&r)[2][4]) {
;     const int lane = fq * 16 + fr;
;     const float rA = rowscale(ss, rowbase + lane), rB = rowscale(ss, rowbase + 128 + lane);
; #pragma unroll
;     for (int m = 0; m < 4; ++m) { r[0][m] = __shfl(rA, m * 16 + fr); r[1][m] = __shfl(rB, m * 16 + fr); }
; }
;     DI void operator()(const pg8::f32x4 (&acc)[2][2][4][2], const pg8::Unit& u, int wr, int wc, int fr, int fq) const {
;         const int row0 = u.pm * 256 + wr * 64 + fr, col0 = u.pn * 256 + wc * 32 + 8 * fq;
;         float rs[2][4]; rowscales8(ss, u.pm * 256 + wr * 64, fr, fq, rs);
; #pragma unroll
;         for (int ai = 0; ai < 2; ++ai)
; #pragma unroll
;             for (int m = 0; m < 4; ++m) {
;                 const int row = row0 + ai * 128 + m * 16; const float r = rs[ai][m];
;                 float part = 0.f;
; #pragma unroll
;                 for (int bj = 0; bj < 2; ++bj) { const size_t off = (size_t)row * 1024 + col0 + bj * 128;
;                     const u32x4 tw = *(const u32x4*)(T + off); const u32x4 xw = *(const u32x4*)(xr + off);
;                     const pg8::f32x4 a0 = acc[ai][bj][m][0] * r, a1 = acc[ai][bj][m][1] * r;
;                     const float o0 = lo16(xw.x) + lo16(tw.x) * __frcp_rn(1.0f + __expf(-a0[0])), o1 = hi16(xw.x) + hi16(tw.x) * __frcp_rn(1.0f + __expf(-a0[1]));
;                     const float o2 = lo16(xw.y) + lo16(tw.y) * __frcp_rn(1.0f + __expf(-a0[2])), o3 = hi16(xw.y) + hi16(tw.y) * __frcp_rn(1.0f + __expf(-a0[3]));
;                     const float o4 = lo16(xw.z) + lo16(tw.z) * __frcp_rn(1.0f + __expf(-a1[0])), o5 = hi16(xw.z) + hi16(tw.z) * __frcp_rn(1.0f + __expf(-a1[1]));
;                     const float o6 = lo16(xw.w) + lo16(tw.w) * __frcp_rn(1.0f + __expf(-a1[2])), o7 = hi16(xw.w) + hi16(tw.w) * __frcp_rn(1.0f + __expf(-a1[3]));
.LBB0_470:
	v_mov_b32_e32 v240, 0xbfb8aa3b
	s_lshl_b32 s1, s2, 8
	s_add_i32 s1, s1, s80
	v_or_b32_e32 v154, s1, v139
	v_ashrrev_i32_e32 v155, 31, v154
	v_lshlrev_b64 v[154:155], 6, v[154:155]
	v_lshl_add_u64 v[158:159], s[8:9], 0, v[154:155]
	global_load_dwordx4 v[154:157], v[158:159], off offset:16
	global_load_dwordx4 v[162:165], v[158:159], off offset:48
	global_load_dwordx4 v[166:169], v[158:159], off
	global_load_dwordx4 v[170:173], v[158:159], off offset:32
	v_add_u32_e32 v232, s1, v151
	v_ashrrev_i32_e32 v233, 31, v232
	v_lshlrev_b64 v[232:233], 6, v[232:233]
	v_lshl_add_u64 v[230:231], s[8:9], 0, v[232:233]
	global_load_dwordx4 v[214:217], v[230:231], off offset:16
	global_load_dwordx4 v[218:221], v[230:231], off offset:48
	global_load_dwordx4 v[222:225], v[230:231], off
	global_load_dwordx4 v[226:229], v[230:231], off offset:32
	s_mov_b32 s2, 0x3a800000
	v_or_b32_e32 v142, s1, v145
	v_lshl_or_b32 v140, s0, 8, v149
	s_waitcnt vmcnt(4)
	v_mov_b32_e32 v158, v166
	v_mov_b32_e32 v159, v170
	v_mov_b32_e32 v170, v167
	v_mov_b32_e32 v166, v168
	v_mov_b32_e32 v167, v172
	v_mov_b32_e32 v172, v169
	v_pk_add_f32 v[158:159], v[158:159], v[170:171]
	v_pk_add_f32 v[166:167], v[166:167], v[172:173]
	v_pk_add_f32 v[158:159], v[158:159], v[166:167]
	v_mov_b32_e32 v166, v154
	v_mov_b32_e32 v167, v162
	v_mov_b32_e32 v162, v155
	v_pk_add_f32 v[154:155], v[166:167], v[162:163]
	v_mov_b32_e32 v162, v156
	v_mov_b32_e32 v163, v164
	v_mov_b32_e32 v164, v157
	v_pk_add_f32 v[156:157], v[162:163], v[164:165]
	v_pk_add_f32 v[154:155], v[154:155], v[156:157]
	v_pk_add_f32 v[158:159], v[158:159], v[154:155]
	s_waitcnt vmcnt(0)
	v_mov_b64_e32 v[154:155], v[214:215]
	v_mov_b64_e32 v[156:157], v[216:217]
	v_mov_b64_e32 v[162:163], v[218:219]
	v_mov_b64_e32 v[164:165], v[220:221]
	v_mov_b64_e32 v[166:167], v[222:223]
	v_mov_b64_e32 v[168:169], v[224:225]
	v_mov_b64_e32 v[170:171], v[226:227]
	v_mov_b64_e32 v[172:173], v[228:229]
	v_mov_b32_e32 v174, v166
	v_mov_b32_e32 v175, v170
	v_mov_b32_e32 v170, v167
	v_pk_add_f32 v[166:167], v[174:175], v[170:171]
	v_mov_b32_e32 v170, v168
	v_mov_b32_e32 v171, v172
	v_mov_b32_e32 v172, v169
	v_pk_add_f32 v[168:169], v[170:171], v[172:173]
	v_pk_add_f32 v[166:167], v[166:167], v[168:169]
	v_mov_b32_e32 v168, v154
	v_mov_b32_e32 v169, v162
	v_mov_b32_e32 v162, v155
	v_pk_add_f32 v[154:155], v[168:169], v[162:163]
	v_mov_b32_e32 v162, v156
	v_mov_b32_e32 v163, v164
	v_mov_b32_e32 v164, v157
	v_pk_add_f32 v[156:157], v[162:163], v[164:165]
	v_pk_add_f32 v[154:155], v[154:155], v[156:157]
	v_mov_b32_e32 v157, v158
	v_pk_add_f32 v[154:155], v[166:167], v[154:155]
	v_mov_b32_e32 v156, v154
	v_mov_b32_e32 v158, v155
	v_pk_add_f32 v[154:155], v[156:157], v[158:159]
	v_pk_fma_f32 v[154:155], v[154:155], s[2:3], v[176:177] op_sel_hi:[1,0,0]
	v_mul_f32_e32 v138, 0x4b800000, v155
	v_cmp_gt_f32_e64 s[42:43], s39, v155
	v_cmp_gt_f32_e32 vcc, s39, v154
	s_nop 0
	v_cndmask_b32_e64 v138, v155, v138, s[42:43]
	v_rsq_f32_e32 v138, v138
	s_nop 0
	v_mul_f32_e32 v141, 0x45800000, v138
	v_cndmask_b32_e64 v138, v138, v141, s[42:43]
	v_mul_f32_e32 v141, 0x4b800000, v154
	v_cndmask_b32_e32 v141, v154, v141, vcc
	v_rsq_f32_e32 v141, v141
	s_lshl_b32 s42, s0, 2
	s_ashr_i32 s43, s42, 31
	v_mul_f32_e32 v143, 0x45800000, v141
	v_cndmask_b32_e32 v141, v141, v143, vcc
	v_and_b32_e32 v143, 64, v177
	v_or_b32_e32 v144, v143, v145
	v_lshlrev_b32_e32 v155, 2, v144
	ds_bpermute_b32 v168, v155, v138
	ds_bpermute_b32 v148, v155, v141
	ds_bpermute_b32 v154, v155, v138 offset:64
	ds_bpermute_b32 v146, v155, v141 offset:64
	ds_bpermute_b32 v152, v155, v138 offset:128
	ds_bpermute_b32 v144, v155, v141 offset:128
	ds_bpermute_b32 v150, v155, v138 offset:192
	ds_bpermute_b32 v138, v155, v141 offset:192
	v_xor_b32_e32 v155, 16, v177
	v_add_u32_e32 v143, 64, v143
	v_cmp_lt_i32_e32 vcc, v155, v143
	v_ashrrev_i32_e32 v141, 31, v140
	s_nop 0
	v_cndmask_b32_e32 v155, v177, v155, vcc
	v_lshlrev_b32_e32 v169, 2, v155
	v_xor_b32_e32 v155, 32, v177
	v_cmp_lt_i32_e32 vcc, v155, v143
	s_waitcnt lgkmcnt(7)
	v_pk_mul_f32 v[124:125], v[124:125], v[168:169] op_sel_hi:[1,0]
	v_pk_mul_f32 v[126:127], v[126:127], v[168:169] op_sel_hi:[1,0]
	v_cndmask_b32_e32 v143, v177, v155, vcc
	v_lshlrev_b32_e32 v155, 2, v143
	v_ashrrev_i32_e32 v143, 31, v142
	v_lshlrev_b64 v[156:157], 10, v[142:143]
	v_lshl_add_u64 v[156:157], v[156:157], 0, v[140:141]
	v_lshlrev_b64 v[158:159], 1, v[156:157]
	v_lshl_add_u64 v[156:157], s[18:19], 0, v[158:159]
	global_load_dwordx4 v[162:165], v[156:157], off
	v_lshl_add_u64 v[170:171], s[12:13], 0, v[158:159]
	global_load_dwordx4 v[172:175], v[170:171], off
	v_mul_f32_e32 v124, 0xbfb8aa3b, v124
	v_mul_f32_e32 v125, 0xbfb8aa3b, v125
	v_exp_f32_e32 v124, v124
	v_exp_f32_e32 v125, v125
	v_mul_f32_e32 v126, 0xbfb8aa3b, v126
	v_mul_f32_e32 v127, 0xbfb8aa3b, v127
	v_exp_f32_e32 v126, v126
	v_pk_add_f32 v[124:125], v[124:125], 1.0 op_sel_hi:[1,0]
	v_exp_f32_e32 v127, v127
	v_pk_mul_f32 v[120:121], v[120:121], v[168:169] op_sel_hi:[1,0]
	v_pk_mul_f32 v[122:123], v[122:123], v[168:169] op_sel_hi:[1,0]
	v_mul_f32_e32 v120, 0xbfb8aa3b, v120
	v_pk_add_f32 v[126:127], v[126:127], 1.0 op_sel_hi:[1,0]
	v_mul_f32_e32 v121, 0xbfb8aa3b, v121
	v_exp_f32_e32 v120, v120
	v_exp_f32_e32 v121, v121
	v_pk_mul_f32 v[116:117], v[116:117], v[168:169] op_sel_hi:[1,0]
	v_pk_mul_f32 v[118:119], v[118:119], v[168:169] op_sel_hi:[1,0]
	v_pk_mul_f32 v[114:115], v[114:115], v[168:169] op_sel_hi:[1,0]
	v_pk_add_f32 v[120:121], v[120:121], 1.0 op_sel_hi:[1,0]
	v_mul_f32_e32 v114, 0xbfb8aa3b, v114
	v_mul_f32_e32 v115, 0xbfb8aa3b, v115
	v_exp_f32_e32 v114, v114
	v_exp_f32_e32 v115, v115
	s_waitcnt vmcnt(1)
; DI unsigned pk2(float lo, float hi) { const f32x2_t v = {lo, hi}; const bf16x2_t b = __builtin_convertvector(v, bf16x2_t); return __builtin_bit_cast(unsigned, b); }
; DI float lo16(unsigned w) { return __uint_as_float(w << 16); }
; DI float hi16(unsigned w) { return __uint_as_float(w & 0xffff0000u); }
;     DI void operator()(const pg8::f32x4 (&acc)[2][2][4][2], const pg8::Unit& u, int wr, int wc, int fr, int fq) const {
;     ...
;                 for (int bj = 0; bj < 2; ++bj) { const size_t off = (size_t)row * 1024 + col0 + bj * 128;
;                     const u32x4 tw = *(const u32x4*)(T + off); const u32x4 xw = *(const u32x4*)(xr + off);
;                     const pg8::f32x4 a0 = acc[ai][bj][m][0] * r, a1 = acc[ai][bj][m][1] * r;
;                     const float o0 = lo16(xw.x) + lo16(tw.x) * __frcp_rn(1.0f + __expf(-a0[0])), o1 = hi16(xw.x) + hi16(tw.x) * __frcp_rn(1.0f + __expf(-a0[1]));
;                     const float o2 = lo16(xw.y) + lo16(tw.y) * __frcp_rn(1.0f + __expf(-a0[2])), o3 = hi16(xw.y) + hi16(tw.y) * __frcp_rn(1.0f + __expf(-a0[3]));
;                     const float o4 = lo16(xw.z) + lo16(tw.z) * __frcp_rn(1.0f + __expf(-a1[0])), o5 = hi16(xw.z) + hi16(tw.z) * __frcp_rn(1.0f + __expf(-a1[1]));
;                     const float o6 = lo16(xw.w) + lo16(tw.w) * __frcp_rn(1.0f + __expf(-a1[2])), o7 = hi16(xw.w) + hi16(tw.w) * __frcp_rn(1.0f + __expf(-a1[3]));
;                     u32x4 w; w.x = pk2(o0, o1); w.y = pk2(o2, o3); w.z = pk2(o4, o5); w.w = pk2(o6, o7); *(u32x4*)(xbo + off) = w;
;                     part += ((o0 * o0 + o1 * o1) + (o2 * o2 + o3 * o3)) + ((o4 * o4 + o5 * o5) + (o6 * o6 + o7 * o7)); }
;                 part += __shfl_xor(part, 16); part += __shfl_xor(part, 32);
;                 if (ssout && fq == 0) ssout[(size_t)row * 16 + u.pn * 4 + wc] = part;
	v_lshlrev_b32_e32 v166, 16, v162
	v_and_b32_e32 v167, 0xffff0000, v162
	s_waitcnt vmcnt(0)
	v_lshlrev_b32_e32 v158, 16, v172
	v_and_b32_e32 v159, 0xffff0000, v172
	v_pk_add_f32 v[114:115], v[114:115], 1.0 op_sel_hi:[1,0]
	v_rcp_f32_e32 v125, v125
	v_rcp_f32_e32 v124, v124
	s_nop 0
	v_pk_fma_f32 v[124:125], v[124:125], v[166:167], v[158:159]
	v_lshlrev_b32_e32 v158, 16, v173
	v_and_b32_e32 v159, 0xffff0000, v173
	v_lshlrev_b32_e32 v162, 16, v163
	v_rcp_f32_e32 v127, v127
	v_and_b32_e32 v163, 0xffff0000, v163
	v_rcp_f32_e32 v126, v126
	s_nop 0
	v_pk_fma_f32 v[126:127], v[126:127], v[162:163], v[158:159]
	v_lshlrev_b32_e32 v162, 16, v164
	v_and_b32_e32 v163, 0xffff0000, v164
	v_lshlrev_b32_e32 v158, 16, v174
	v_and_b32_e32 v159, 0xffff0000, v174
	v_rcp_f32_e32 v121, v121
	v_rcp_f32_e32 v120, v120
	s_nop 0
	v_pk_fma_f32 v[166:167], v[120:121], v[162:163], v[158:159]
	v_pk_mul_f32 v[120:121], v[122:123], v[240:241] op_sel_hi:[1,0]
	v_exp_f32_e32 v120, v120
	v_exp_f32_e32 v121, v121
	v_lshlrev_b32_e32 v158, 16, v165
	v_and_b32_e32 v159, 0xffff0000, v165
	v_lshlrev_b32_e32 v122, 16, v175
	v_pk_add_f32 v[120:121], v[120:121], 1.0 op_sel_hi:[1,0]
	v_and_b32_e32 v123, 0xffff0000, v175
	v_rcp_f32_e32 v121, v121
	v_rcp_f32_e32 v120, v120
	s_nop 0
	v_pk_fma_f32 v[172:173], v[120:121], v[158:159], v[122:123]
	v_cvt_pk_bf16_f32 v120, v124, v125
	v_cvt_pk_bf16_f32 v121, v126, v127
	v_cvt_pk_bf16_f32 v122, v166, v167
	v_cvt_pk_bf16_f32 v123, v172, v173
	global_store_dwordx4 v[156:157], v[120:123], off
	v_pk_mul_f32 v[158:159], v[124:125], v[124:125]
	v_pk_mul_f32 v[162:163], v[126:127], v[126:127]
	global_load_dwordx4 v[120:123], v[156:157], off offset:256
	global_load_dwordx4 v[124:127], v[170:171], off offset:256
	v_pk_mul_f32 v[170:171], v[112:113], v[168:169] op_sel_hi:[1,0]
	v_pk_mul_f32 v[112:113], v[116:117], v[240:241] op_sel_hi:[1,0]
	v_exp_f32_e32 v112, v112
	v_exp_f32_e32 v113, v113
	v_pk_mul_f32 v[164:165], v[166:167], v[166:167]
	v_pk_mul_f32 v[166:167], v[172:173], v[172:173]
	v_pk_add_f32 v[112:113], v[112:113], 1.0 op_sel_hi:[1,0]
	s_waitcnt vmcnt(1)
	v_lshlrev_b32_e32 v172, 16, v120
	v_and_b32_e32 v173, 0xffff0000, v120
	s_waitcnt vmcnt(0)
	v_lshlrev_b32_e32 v116, 16, v124
	v_and_b32_e32 v117, 0xffff0000, v124
	v_rcp_f32_e32 v113, v113
	v_rcp_f32_e32 v112, v112
	s_nop 0
	v_pk_fma_f32 v[112:113], v[112:113], v[172:173], v[116:117]
	v_pk_mul_f32 v[116:117], v[118:119], v[240:241] op_sel_hi:[1,0]
	v_exp_f32_e32 v116, v116
	v_exp_f32_e32 v117, v117
	v_lshlrev_b32_e32 v118, 16, v125
	v_and_b32_e32 v119, 0xffff0000, v125
	v_lshlrev_b32_e32 v120, 16, v121
	v_pk_add_f32 v[116:117], v[116:117], 1.0 op_sel_hi:[1,0]
	v_and_b32_e32 v121, 0xffff0000, v121
	v_rcp_f32_e32 v117, v117
	v_rcp_f32_e32 v116, v116
	s_nop 0
	v_pk_fma_f32 v[116:117], v[116:117], v[120:121], v[118:119]
	v_pk_mul_f32 v[118:119], v[170:171], v[240:241] op_sel_hi:[1,0]
	v_exp_f32_e32 v118, v118
	v_exp_f32_e32 v119, v119
	v_lshlrev_b32_e32 v124, 16, v122
	v_and_b32_e32 v125, 0xffff0000, v122
	v_lshlrev_b32_e32 v120, 16, v126
	v_pk_add_f32 v[118:119], v[118:119], 1.0 op_sel_hi:[1,0]
	v_and_b32_e32 v121, 0xffff0000, v126
	v_rcp_f32_e32 v119, v119
	v_rcp_f32_e32 v118, v118
	s_nop 0
	v_pk_fma_f32 v[124:125], v[118:119], v[124:125], v[120:121]
	v_lshlrev_b32_e32 v120, 16, v123
	v_and_b32_e32 v121, 0xffff0000, v123
	v_lshlrev_b32_e32 v118, 16, v127
	v_and_b32_e32 v119, 0xffff0000, v127
	v_rcp_f32_e32 v115, v115
	v_rcp_f32_e32 v114, v114
	s_nop 0
	v_pk_fma_f32 v[114:115], v[114:115], v[120:121], v[118:119]
	v_cvt_pk_bf16_f32 v118, v112, v113
	v_cvt_pk_bf16_f32 v119, v116, v117
	v_cvt_pk_bf16_f32 v120, v124, v125
	v_cvt_pk_bf16_f32 v121, v114, v115
	global_store_dwordx4 v[156:157], v[118:121], off offset:256
	v_pk_mul_f32 v[114:115], v[114:115], v[114:115]
	v_pk_mul_f32 v[112:113], v[112:113], v[112:113]
	v_pk_mul_f32 v[118:119], v[124:125], v[124:125]
	v_pk_mul_f32 v[116:117], v[116:117], v[116:117]
	v_add_f32_e32 v120, v166, v167
	v_add_f32_e32 v121, v164, v165
	v_add_f32_e32 v114, v114, v115
	v_add_f32_e32 v115, v118, v119
	v_add_f32_e32 v120, v121, v120
	v_add_f32_e32 v121, v162, v163
	v_add_f32_e32 v122, v158, v159
	v_add_f32_e32 v114, v115, v114
	v_add_f32_e32 v115, v116, v117
	v_add_f32_e32 v112, v112, v113
	v_add_f32_e32 v121, v122, v121
	v_add_f32_e32 v112, v112, v115
	v_add_f32_e32 v120, v121, v120
	v_add_f32_e32 v112, v112, v114
	v_add_f32_e32 v112, v120, v112
	ds_bpermute_b32 v113, v169, v112
	s_waitcnt lgkmcnt(0)
	v_add_f32_e32 v112, v112, v113
	ds_bpermute_b32 v113, v155, v112
	s_and_saveexec_b64 s[0:1], s[46:47]
	s_cbranch_execz .LBB0_472
	s_waitcnt lgkmcnt(0)
	v_add_f32_e32 v114, v112, v113
	v_lshlrev_b64 v[112:113], 6, v[142:143]
	v_lshl_add_u64 v[112:113], s[6:7], 0, v[112:113]
	v_lshl_add_u64 v[112:113], s[42:43], 2, v[112:113]
	s_lshl_b32 s94, s35, 2
	v_lshl_add_u64 v[112:113], v[112:113], 0, s[94:95]
	global_store_dword v[112:113], v114, off
; DI unsigned pk2(float lo, float hi) { const f32x2_t v = {lo, hi}; const bf16x2_t b = __builtin_convertvector(v, bf16x2_t); return __builtin_bit_cast(unsigned, b); }
; DI float lo16(unsigned w) { return __uint_as_float(w << 16); }
; DI float hi16(unsigned w) { return __uint_as_float(w & 0xffff0000u); }
;     DI void operator()(const pg8::f32x4 (&acc)[2][2][4][2], const pg8::Unit& u, int wr, int wc, int fr, int fq) const {
;     ...
;                 for (int bj = 0; bj < 2; ++bj) { const size_t off = (size_t)row * 1024 + col0 + bj * 128;
;                     const u32x4 tw = *(const u32x4*)(T + off); const u32x4 xw = *(const u32x4*)(xr + off);
;                     const pg8::f32x4 a0 = acc[ai][bj][m][0] * r, a1 = acc[ai][bj][m][1] * r;
;                     const float o0 = lo16(xw.x) + lo16(tw.x) * __frcp_rn(1.0f + __expf(-a0[0])), o1 = hi16(xw.x) + hi16(tw.x) * __frcp_rn(1.0f + __expf(-a0[1]));
;                     const float o2 = lo16(xw.y) + lo16(tw.y) * __frcp_rn(1.0f + __expf(-a0[2])), o3 = hi16(xw.y) + hi16(tw.y) * __frcp_rn(1.0f + __expf(-a0[3]));
;                     const float o4 = lo16(xw.z) + lo16(tw.z) * __frcp_rn(1.0f + __expf(-a1[0])), o5 = hi16(xw.z) + hi16(tw.z) * __frcp_rn(1.0f + __expf(-a1[1]));
;                     const float o6 = lo16(xw.w) + lo16(tw.w) * __frcp_rn(1.0f + __expf(-a1[2])), o7 = hi16(xw.w) + hi16(tw.w) * __frcp_rn(1.0f + __expf(-a1[3]));
;                     u32x4 w; w.x = pk2(o0, o1); w.y = pk2(o2, o3); w.z = pk2(o4, o5); w.w = pk2(o6, o7); *(u32x4*)(xbo + off) = w;
;                     part += ((o0 * o0 + o1 * o1) + (o2 * o2 + o3 * o3)) + ((o4 * o4 + o5 * o5) + (o6 * o6 + o7 * o7)); }
;                 part += __shfl_xor(part, 16); part += __shfl_xor(part, 32);
;                 if (ssout && fq == 0) ssout[(size_t)row * 16 + u.pn * 4 + wc] = part;
.LBB0_472:
	s_or_b64 exec, exec, s[0:1]
	v_or_b32_e32 v120, 16, v142
	v_ashrrev_i32_e32 v121, 31, v120
	s_waitcnt lgkmcnt(0)
	v_lshlrev_b64 v[112:113], 10, v[120:121]
	v_lshl_add_u64 v[112:113], v[112:113], 0, v[140:141]
	v_lshlrev_b64 v[116:117], 1, v[112:113]
	v_lshl_add_u64 v[122:123], s[18:19], 0, v[116:117]
	global_load_dwordx4 v[112:115], v[122:123], off
	v_lshl_add_u64 v[124:125], s[12:13], 0, v[116:117]
	global_load_dwordx4 v[116:119], v[124:125], off
	v_pk_mul_f32 v[108:109], v[108:109], v[154:155] op_sel_hi:[1,0]
	v_pk_mul_f32 v[126:127], v[104:105], v[154:155] op_sel_hi:[1,0]
	v_pk_mul_f32 v[104:105], v[108:109], v[240:241] op_sel_hi:[1,0]
	v_exp_f32_e32 v104, v104
	v_exp_f32_e32 v105, v105
	v_pk_mul_f32 v[110:111], v[110:111], v[154:155] op_sel_hi:[1,0]
	v_pk_mul_f32 v[106:107], v[106:107], v[154:155] op_sel_hi:[1,0]
	v_pk_mul_f32 v[100:101], v[100:101], v[154:155] op_sel_hi:[1,0]
	v_pk_add_f32 v[104:105], v[104:105], 1.0 op_sel_hi:[1,0]
	v_mul_f32_e32 v106, 0xbfb8aa3b, v106
	v_mul_f32_e32 v107, 0xbfb8aa3b, v107
	v_exp_f32_e32 v106, v106
	v_exp_f32_e32 v107, v107
	v_pk_mul_f32 v[102:103], v[102:103], v[154:155] op_sel_hi:[1,0]
	v_pk_mul_f32 v[98:99], v[98:99], v[154:155] op_sel_hi:[1,0]
	v_pk_add_f32 v[106:107], v[106:107], 1.0 op_sel_hi:[1,0]
	v_mul_f32_e32 v98, 0xbfb8aa3b, v98
	v_mul_f32_e32 v99, 0xbfb8aa3b, v99
	v_exp_f32_e32 v98, v98
	v_exp_f32_e32 v99, v99
	s_waitcnt vmcnt(1)
	v_lshlrev_b32_e32 v156, 16, v112
	v_and_b32_e32 v157, 0xffff0000, v112
	s_waitcnt vmcnt(0)
	v_lshlrev_b32_e32 v108, 16, v116
	v_and_b32_e32 v109, 0xffff0000, v116
	v_pk_add_f32 v[98:99], v[98:99], 1.0 op_sel_hi:[1,0]
	v_rcp_f32_e32 v105, v105
	v_rcp_f32_e32 v104, v104
	s_nop 0
	v_pk_fma_f32 v[104:105], v[104:105], v[156:157], v[108:109]
	v_pk_mul_f32 v[108:109], v[110:111], v[240:241] op_sel_hi:[1,0]
	v_exp_f32_e32 v108, v108
	v_exp_f32_e32 v109, v109
	v_lshlrev_b32_e32 v110, 16, v117
	v_and_b32_e32 v111, 0xffff0000, v117
	v_lshlrev_b32_e32 v112, 16, v113
	v_pk_add_f32 v[108:109], v[108:109], 1.0 op_sel_hi:[1,0]
	v_and_b32_e32 v113, 0xffff0000, v113
	v_rcp_f32_e32 v109, v109
	v_rcp_f32_e32 v108, v108
	s_nop 0
	v_pk_fma_f32 v[110:111], v[108:109], v[112:113], v[110:111]
	v_pk_mul_f32 v[108:109], v[126:127], v[240:241] op_sel_hi:[1,0]
	v_exp_f32_e32 v108, v108
	v_exp_f32_e32 v109, v109
	v_lshlrev_b32_e32 v116, 16, v114
	v_and_b32_e32 v117, 0xffff0000, v114
	v_lshlrev_b32_e32 v112, 16, v118
	v_pk_add_f32 v[108:109], v[108:109], 1.0 op_sel_hi:[1,0]
	v_and_b32_e32 v113, 0xffff0000, v118
	v_rcp_f32_e32 v109, v109
	v_rcp_f32_e32 v108, v108
	s_nop 0
	v_pk_fma_f32 v[116:117], v[108:109], v[116:117], v[112:113]
	v_lshlrev_b32_e32 v112, 16, v115
	v_and_b32_e32 v113, 0xffff0000, v115
	v_lshlrev_b32_e32 v108, 16, v119
	v_and_b32_e32 v109, 0xffff0000, v119
	v_rcp_f32_e32 v107, v107
	v_rcp_f32_e32 v106, v106
	s_nop 0
	v_pk_fma_f32 v[118:119], v[106:107], v[112:113], v[108:109]
	v_cvt_pk_bf16_f32 v106, v104, v105
	v_cvt_pk_bf16_f32 v107, v110, v111
	v_cvt_pk_bf16_f32 v108, v116, v117
	v_cvt_pk_bf16_f32 v109, v118, v119
	global_store_dwordx4 v[122:123], v[106:109], off
	v_pk_mul_f32 v[112:113], v[104:105], v[104:105]
	v_pk_mul_f32 v[114:115], v[110:111], v[110:111]
	global_load_dwordx4 v[104:107], v[122:123], off offset:256
	global_load_dwordx4 v[108:111], v[124:125], off offset:256
	v_pk_mul_f32 v[124:125], v[96:97], v[154:155] op_sel_hi:[1,0]
	v_pk_mul_f32 v[96:97], v[100:101], v[240:241] op_sel_hi:[1,0]
	v_exp_f32_e32 v96, v96
	v_exp_f32_e32 v97, v97
	v_pk_mul_f32 v[116:117], v[116:117], v[116:117]
	v_pk_mul_f32 v[118:119], v[118:119], v[118:119]
	v_pk_add_f32 v[96:97], v[96:97], 1.0 op_sel_hi:[1,0]
	s_waitcnt vmcnt(1)
	v_lshlrev_b32_e32 v126, 16, v104
	v_and_b32_e32 v127, 0xffff0000, v104
	s_waitcnt vmcnt(0)
	v_lshlrev_b32_e32 v100, 16, v108
	v_and_b32_e32 v101, 0xffff0000, v108
	v_rcp_f32_e32 v97, v97
	v_rcp_f32_e32 v96, v96
	s_nop 0
	v_pk_fma_f32 v[96:97], v[96:97], v[126:127], v[100:101]
	v_pk_mul_f32 v[100:101], v[102:103], v[240:241] op_sel_hi:[1,0]
	v_exp_f32_e32 v100, v100
	v_exp_f32_e32 v101, v101
	v_lshlrev_b32_e32 v102, 16, v109
	v_and_b32_e32 v103, 0xffff0000, v109
	v_lshlrev_b32_e32 v104, 16, v105
	v_pk_add_f32 v[100:101], v[100:101], 1.0 op_sel_hi:[1,0]
	v_and_b32_e32 v105, 0xffff0000, v105
	v_rcp_f32_e32 v101, v101
	v_rcp_f32_e32 v100, v100
	s_nop 0
	v_pk_fma_f32 v[100:101], v[100:101], v[104:105], v[102:103]
	v_pk_mul_f32 v[102:103], v[124:125], v[240:241] op_sel_hi:[1,0]
	v_exp_f32_e32 v102, v102
	v_exp_f32_e32 v103, v103
	v_lshlrev_b32_e32 v108, 16, v106
	v_and_b32_e32 v109, 0xffff0000, v106
	v_lshlrev_b32_e32 v104, 16, v110
	v_pk_add_f32 v[102:103], v[102:103], 1.0 op_sel_hi:[1,0]
	v_and_b32_e32 v105, 0xffff0000, v110
	v_rcp_f32_e32 v103, v103
	v_rcp_f32_e32 v102, v102
	s_nop 0
	v_pk_fma_f32 v[108:109], v[102:103], v[108:109], v[104:105]
	v_lshlrev_b32_e32 v104, 16, v107
	v_and_b32_e32 v105, 0xffff0000, v107
	v_lshlrev_b32_e32 v102, 16, v111
	v_and_b32_e32 v103, 0xffff0000, v111
	v_rcp_f32_e32 v99, v99
	v_rcp_f32_e32 v98, v98
	s_nop 0
	v_pk_fma_f32 v[98:99], v[98:99], v[104:105], v[102:103]
	v_cvt_pk_bf16_f32 v102, v96, v97
	v_cvt_pk_bf16_f32 v103, v100, v101
	v_cvt_pk_bf16_f32 v104, v108, v109
	v_cvt_pk_bf16_f32 v105, v98, v99
	global_store_dwordx4 v[122:123], v[102:105], off offset:256
	v_pk_mul_f32 v[98:99], v[98:99], v[98:99]
	v_pk_mul_f32 v[96:97], v[96:97], v[96:97]
	v_pk_mul_f32 v[102:103], v[108:109], v[108:109]
	v_pk_mul_f32 v[100:101], v[100:101], v[100:101]
	v_add_f32_e32 v104, v118, v119
	v_add_f32_e32 v105, v116, v117
	v_add_f32_e32 v98, v98, v99
	v_add_f32_e32 v99, v102, v103
	v_add_f32_e32 v104, v105, v104
	v_add_f32_e32 v105, v114, v115
	v_add_f32_e32 v106, v112, v113
	v_add_f32_e32 v98, v99, v98
	v_add_f32_e32 v99, v100, v101
	v_add_f32_e32 v96, v96, v97
	v_add_f32_e32 v105, v106, v105
	v_add_f32_e32 v96, v96, v99
	v_add_f32_e32 v104, v105, v104
	v_add_f32_e32 v96, v96, v98
	v_add_f32_e32 v96, v104, v96
	ds_bpermute_b32 v97, v169, v96
	s_waitcnt lgkmcnt(0)
	v_add_f32_e32 v96, v96, v97
	ds_bpermute_b32 v97, v155, v96
	s_and_saveexec_b64 s[0:1], s[46:47]
	s_cbranch_execz .LBB0_474
	s_waitcnt lgkmcnt(0)
	v_add_f32_e32 v98, v96, v97
	v_lshlrev_b64 v[96:97], 6, v[120:121]
	v_lshl_add_u64 v[96:97], s[6:7], 0, v[96:97]
	v_lshl_add_u64 v[96:97], s[42:43], 2, v[96:97]
	s_lshl_b32 s94, s35, 2
	v_lshl_add_u64 v[96:97], v[96:97], 0, s[94:95]
	global_store_dword v[96:97], v98, off
; DI unsigned pk2(float lo, float hi) { const f32x2_t v = {lo, hi}; const bf16x2_t b = __builtin_convertvector(v, bf16x2_t); return __builtin_bit_cast(unsigned, b); }
; DI float lo16(unsigned w) { return __uint_as_float(w << 16); }
; DI float hi16(unsigned w) { return __uint_as_float(w & 0xffff0000u); }
;     DI void operator()(const pg8::f32x4 (&acc)[2][2][4][2], const pg8::Unit& u, int wr, int wc, int fr, int fq) const {
;     ...
;                 for (int bj = 0; bj < 2; ++bj) { const size_t off = (size_t)row * 1024 + col0 + bj * 128;
;                     const u32x4 tw = *(const u32x4*)(T + off); const u32x4 xw = *(const u32x4*)(xr + off);
;                     const pg8::f32x4 a0 = acc[ai][bj][m][0] * r, a1 = acc[ai][bj][m][1] * r;
;                     const float o0 = lo16(xw.x) + lo16(tw.x) * __frcp_rn(1.0f + __expf(-a0[0])), o1 = hi16(xw.x) + hi16(tw.x) * __frcp_rn(1.0f + __expf(-a0[1]));
;                     const float o2 = lo16(xw.y) + lo16(tw.y) * __frcp_rn(1.0f + __expf(-a0[2])), o3 = hi16(xw.y) + hi16(tw.y) * __frcp_rn(1.0f + __expf(-a0[3]));
;                     const float o4 = lo16(xw.z) + lo16(tw.z) * __frcp_rn(1.0f + __expf(-a1[0])), o5 = hi16(xw.z) + hi16(tw.z) * __frcp_rn(1.0f + __expf(-a1[1]));
;                     const float o6 = lo16(xw.w) + lo16(tw.w) * __frcp_rn(1.0f + __expf(-a1[2])), o7 = hi16(xw.w) + hi16(tw.w) * __frcp_rn(1.0f + __expf(-a1[3]));
;                     u32x4 w; w.x = pk2(o0, o1); w.y = pk2(o2, o3); w.z = pk2(o4, o5); w.w = pk2(o6, o7); *(u32x4*)(xbo + off) = w;
;                     part += ((o0 * o0 + o1 * o1) + (o2 * o2 + o3 * o3)) + ((o4 * o4 + o5 * o5) + (o6 * o6 + o7 * o7)); }
;                 part += __shfl_xor(part, 16); part += __shfl_xor(part, 32);
;                 if (ssout && fq == 0) ssout[(size_t)row * 16 + u.pn * 4 + wc] = part;
.LBB0_474:
	s_or_b64 exec, exec, s[0:1]
	v_or_b32_e32 v104, 32, v142
	v_ashrrev_i32_e32 v105, 31, v104
	s_waitcnt lgkmcnt(0)
	v_lshlrev_b64 v[96:97], 10, v[104:105]
	v_lshl_add_u64 v[96:97], v[96:97], 0, v[140:141]
	v_lshlrev_b64 v[100:101], 1, v[96:97]
	v_lshl_add_u64 v[106:107], s[18:19], 0, v[100:101]
	global_load_dwordx4 v[96:99], v[106:107], off
	v_lshl_add_u64 v[108:109], s[12:13], 0, v[100:101]
	global_load_dwordx4 v[100:103], v[108:109], off
	v_pk_mul_f32 v[92:93], v[92:93], v[152:153] op_sel_hi:[1,0]
	v_pk_mul_f32 v[110:111], v[88:89], v[152:153] op_sel_hi:[1,0]
	v_pk_mul_f32 v[88:89], v[92:93], v[240:241] op_sel_hi:[1,0]
	v_exp_f32_e32 v88, v88
	v_exp_f32_e32 v89, v89
	v_pk_mul_f32 v[94:95], v[94:95], v[152:153] op_sel_hi:[1,0]
	v_pk_mul_f32 v[90:91], v[90:91], v[152:153] op_sel_hi:[1,0]
	v_pk_mul_f32 v[84:85], v[84:85], v[152:153] op_sel_hi:[1,0]
	v_pk_add_f32 v[88:89], v[88:89], 1.0 op_sel_hi:[1,0]
	v_mul_f32_e32 v90, 0xbfb8aa3b, v90
	v_mul_f32_e32 v91, 0xbfb8aa3b, v91
	v_exp_f32_e32 v90, v90
	v_exp_f32_e32 v91, v91
	v_pk_mul_f32 v[86:87], v[86:87], v[152:153] op_sel_hi:[1,0]
	v_pk_mul_f32 v[82:83], v[82:83], v[152:153] op_sel_hi:[1,0]
	v_pk_add_f32 v[90:91], v[90:91], 1.0 op_sel_hi:[1,0]
	v_mul_f32_e32 v82, 0xbfb8aa3b, v82
	v_mul_f32_e32 v83, 0xbfb8aa3b, v83
	v_exp_f32_e32 v82, v82
	v_exp_f32_e32 v83, v83
	s_waitcnt vmcnt(1)
	v_lshlrev_b32_e32 v112, 16, v96
	v_and_b32_e32 v113, 0xffff0000, v96
	s_waitcnt vmcnt(0)
	v_lshlrev_b32_e32 v92, 16, v100
	v_and_b32_e32 v93, 0xffff0000, v100
	v_pk_add_f32 v[82:83], v[82:83], 1.0 op_sel_hi:[1,0]
	v_rcp_f32_e32 v89, v89
	v_rcp_f32_e32 v88, v88
	s_nop 0
	v_pk_fma_f32 v[88:89], v[88:89], v[112:113], v[92:93]
	v_pk_mul_f32 v[92:93], v[94:95], v[240:241] op_sel_hi:[1,0]
	v_exp_f32_e32 v92, v92
	v_exp_f32_e32 v93, v93
	v_lshlrev_b32_e32 v94, 16, v101
	v_and_b32_e32 v95, 0xffff0000, v101
	v_lshlrev_b32_e32 v96, 16, v97
	v_pk_add_f32 v[92:93], v[92:93], 1.0 op_sel_hi:[1,0]
	v_and_b32_e32 v97, 0xffff0000, v97
	v_rcp_f32_e32 v93, v93
	v_rcp_f32_e32 v92, v92
	s_nop 0
	v_pk_fma_f32 v[94:95], v[92:93], v[96:97], v[94:95]
	v_pk_mul_f32 v[92:93], v[110:111], v[240:241] op_sel_hi:[1,0]
	v_exp_f32_e32 v92, v92
	v_exp_f32_e32 v93, v93
	v_lshlrev_b32_e32 v100, 16, v98
	v_and_b32_e32 v101, 0xffff0000, v98
	v_lshlrev_b32_e32 v96, 16, v102
	v_pk_add_f32 v[92:93], v[92:93], 1.0 op_sel_hi:[1,0]
	v_and_b32_e32 v97, 0xffff0000, v102
	v_rcp_f32_e32 v93, v93
	v_rcp_f32_e32 v92, v92
	s_nop 0
	v_pk_fma_f32 v[100:101], v[92:93], v[100:101], v[96:97]
	v_lshlrev_b32_e32 v96, 16, v99
	v_and_b32_e32 v97, 0xffff0000, v99
	v_lshlrev_b32_e32 v92, 16, v103
	v_and_b32_e32 v93, 0xffff0000, v103
	v_rcp_f32_e32 v91, v91
	v_rcp_f32_e32 v90, v90
	s_nop 0
	v_pk_fma_f32 v[102:103], v[90:91], v[96:97], v[92:93]
	v_cvt_pk_bf16_f32 v90, v88, v89
	v_cvt_pk_bf16_f32 v91, v94, v95
	v_cvt_pk_bf16_f32 v92, v100, v101
	v_cvt_pk_bf16_f32 v93, v102, v103
	global_store_dwordx4 v[106:107], v[90:93], off
	v_pk_mul_f32 v[96:97], v[88:89], v[88:89]
	v_pk_mul_f32 v[98:99], v[94:95], v[94:95]
	global_load_dwordx4 v[88:91], v[106:107], off offset:256
	global_load_dwordx4 v[92:95], v[108:109], off offset:256
	v_pk_mul_f32 v[108:109], v[80:81], v[152:153] op_sel_hi:[1,0]
	v_pk_mul_f32 v[80:81], v[84:85], v[240:241] op_sel_hi:[1,0]
	v_exp_f32_e32 v80, v80
	v_exp_f32_e32 v81, v81
	v_pk_mul_f32 v[100:101], v[100:101], v[100:101]
	v_pk_mul_f32 v[102:103], v[102:103], v[102:103]
	v_pk_add_f32 v[80:81], v[80:81], 1.0 op_sel_hi:[1,0]
	s_waitcnt vmcnt(1)
	v_lshlrev_b32_e32 v110, 16, v88
	v_and_b32_e32 v111, 0xffff0000, v88
	s_waitcnt vmcnt(0)
	v_lshlrev_b32_e32 v84, 16, v92
	v_and_b32_e32 v85, 0xffff0000, v92
	v_rcp_f32_e32 v81, v81
	v_rcp_f32_e32 v80, v80
	s_nop 0
	v_pk_fma_f32 v[80:81], v[80:81], v[110:111], v[84:85]
	v_pk_mul_f32 v[84:85], v[86:87], v[240:241] op_sel_hi:[1,0]
	v_exp_f32_e32 v84, v84
	v_exp_f32_e32 v85, v85
	v_lshlrev_b32_e32 v86, 16, v93
	v_and_b32_e32 v87, 0xffff0000, v93
	v_lshlrev_b32_e32 v88, 16, v89
	v_pk_add_f32 v[84:85], v[84:85], 1.0 op_sel_hi:[1,0]
	v_and_b32_e32 v89, 0xffff0000, v89
	v_rcp_f32_e32 v85, v85
	v_rcp_f32_e32 v84, v84
	s_nop 0
	v_pk_fma_f32 v[84:85], v[84:85], v[88:89], v[86:87]
	v_pk_mul_f32 v[86:87], v[108:109], v[240:241] op_sel_hi:[1,0]
	v_exp_f32_e32 v86, v86
	v_exp_f32_e32 v87, v87
	v_lshlrev_b32_e32 v92, 16, v90
	v_and_b32_e32 v93, 0xffff0000, v90
	v_lshlrev_b32_e32 v88, 16, v94
	v_pk_add_f32 v[86:87], v[86:87], 1.0 op_sel_hi:[1,0]
	v_and_b32_e32 v89, 0xffff0000, v94
	v_rcp_f32_e32 v87, v87
	v_rcp_f32_e32 v86, v86
	s_nop 0
	v_pk_fma_f32 v[92:93], v[86:87], v[92:93], v[88:89]
	v_lshlrev_b32_e32 v88, 16, v91
	v_and_b32_e32 v89, 0xffff0000, v91
	v_lshlrev_b32_e32 v86, 16, v95
	v_and_b32_e32 v87, 0xffff0000, v95
	v_rcp_f32_e32 v83, v83
	v_rcp_f32_e32 v82, v82
	s_nop 0
	v_pk_fma_f32 v[82:83], v[82:83], v[88:89], v[86:87]
	v_cvt_pk_bf16_f32 v86, v80, v81
	v_cvt_pk_bf16_f32 v87, v84, v85
	v_cvt_pk_bf16_f32 v88, v92, v93
	v_cvt_pk_bf16_f32 v89, v82, v83
	global_store_dwordx4 v[106:107], v[86:89], off offset:256
	v_pk_mul_f32 v[82:83], v[82:83], v[82:83]
	v_pk_mul_f32 v[80:81], v[80:81], v[80:81]
	v_pk_mul_f32 v[86:87], v[92:93], v[92:93]
	v_pk_mul_f32 v[84:85], v[84:85], v[84:85]
	v_add_f32_e32 v88, v102, v103
	v_add_f32_e32 v89, v100, v101
	v_add_f32_e32 v82, v82, v83
	v_add_f32_e32 v83, v86, v87
	v_add_f32_e32 v88, v89, v88
	v_add_f32_e32 v89, v98, v99
	v_add_f32_e32 v90, v96, v97
	v_add_f32_e32 v82, v83, v82
	v_add_f32_e32 v83, v84, v85
	v_add_f32_e32 v80, v80, v81
	v_add_f32_e32 v89, v90, v89
	v_add_f32_e32 v80, v80, v83
	v_add_f32_e32 v88, v89, v88
	v_add_f32_e32 v80, v80, v82
	v_add_f32_e32 v80, v88, v80
	ds_bpermute_b32 v81, v169, v80
	s_waitcnt lgkmcnt(0)
	v_add_f32_e32 v80, v80, v81
	ds_bpermute_b32 v81, v155, v80
	s_and_saveexec_b64 s[0:1], s[46:47]
	s_cbranch_execz .LBB0_476
	s_waitcnt lgkmcnt(0)
	v_add_f32_e32 v82, v80, v81
	v_lshlrev_b64 v[80:81], 6, v[104:105]
	v_lshl_add_u64 v[80:81], s[6:7], 0, v[80:81]
	v_lshl_add_u64 v[80:81], s[42:43], 2, v[80:81]
	s_lshl_b32 s94, s35, 2
	v_lshl_add_u64 v[80:81], v[80:81], 0, s[94:95]
	global_store_dword v[80:81], v82, off
; DI unsigned pk2(float lo, float hi) { const f32x2_t v = {lo, hi}; const bf16x2_t b = __builtin_convertvector(v, bf16x2_t); return __builtin_bit_cast(unsigned, b); }
; DI float lo16(unsigned w) { return __uint_as_float(w << 16); }
; DI float hi16(unsigned w) { return __uint_as_float(w & 0xffff0000u); }
;     DI void operator()(const pg8::f32x4 (&acc)[2][2][4][2], const pg8::Unit& u, int wr, int wc, int fr, int fq) const {
;     ...
;                 for (int bj = 0; bj < 2; ++bj) { const size_t off = (size_t)row * 1024 + col0 + bj * 128;
;                     const u32x4 tw = *(const u32x4*)(T + off); const u32x4 xw = *(const u32x4*)(xr + off);
;                     const pg8::f32x4 a0 = acc[ai][bj][m][0] * r, a1 = acc[ai][bj][m][1] * r;
;                     const float o0 = lo16(xw.x) + lo16(tw.x) * __frcp_rn(1.0f + __expf(-a0[0])), o1 = hi16(xw.x) + hi16(tw.x) * __frcp_rn(1.0f + __expf(-a0[1]));
;                     const float o2 = lo16(xw.y) + lo16(tw.y) * __frcp_rn(1.0f + __expf(-a0[2])), o3 = hi16(xw.y) + hi16(tw.y) * __frcp_rn(1.0f + __expf(-a0[3]));
;                     const float o4 = lo16(xw.z) + lo16(tw.z) * __frcp_rn(1.0f + __expf(-a1[0])), o5 = hi16(xw.z) + hi16(tw.z) * __frcp_rn(1.0f + __expf(-a1[1]));
;                     const float o6 = lo16(xw.w) + lo16(tw.w) * __frcp_rn(1.0f + __expf(-a1[2])), o7 = hi16(xw.w) + hi16(tw.w) * __frcp_rn(1.0f + __expf(-a1[3]));
;                     u32x4 w; w.x = pk2(o0, o1); w.y = pk2(o2, o3); w.z = pk2(o4, o5); w.w = pk2(o6, o7); *(u32x4*)(xbo + off) = w;
;                     part += ((o0 * o0 + o1 * o1) + (o2 * o2 + o3 * o3)) + ((o4 * o4 + o5 * o5) + (o6 * o6 + o7 * o7)); }
;                 part += __shfl_xor(part, 16); part += __shfl_xor(part, 32);
;                 if (ssout && fq == 0) ssout[(size_t)row * 16 + u.pn * 4 + wc] = part;
.LBB0_476:
	s_or_b64 exec, exec, s[0:1]
	v_or_b32_e32 v88, 48, v142
	v_ashrrev_i32_e32 v89, 31, v88
	s_waitcnt lgkmcnt(0)
	v_lshlrev_b64 v[80:81], 10, v[88:89]
	v_lshl_add_u64 v[80:81], v[80:81], 0, v[140:141]
	v_lshlrev_b64 v[84:85], 1, v[80:81]
	v_lshl_add_u64 v[90:91], s[18:19], 0, v[84:85]
	global_load_dwordx4 v[80:83], v[90:91], off
	v_lshl_add_u64 v[92:93], s[12:13], 0, v[84:85]
	global_load_dwordx4 v[84:87], v[92:93], off
	v_pk_mul_f32 v[76:77], v[76:77], v[150:151] op_sel_hi:[1,0]
	v_pk_mul_f32 v[94:95], v[72:73], v[150:151] op_sel_hi:[1,0]
	v_pk_mul_f32 v[72:73], v[76:77], v[240:241] op_sel_hi:[1,0]
	v_exp_f32_e32 v72, v72
	v_exp_f32_e32 v73, v73
	v_pk_mul_f32 v[78:79], v[78:79], v[150:151] op_sel_hi:[1,0]
	v_pk_mul_f32 v[74:75], v[74:75], v[150:151] op_sel_hi:[1,0]
	v_pk_mul_f32 v[68:69], v[68:69], v[150:151] op_sel_hi:[1,0]
	v_pk_add_f32 v[72:73], v[72:73], 1.0 op_sel_hi:[1,0]
	v_mul_f32_e32 v74, 0xbfb8aa3b, v74
	v_mul_f32_e32 v75, 0xbfb8aa3b, v75
	v_exp_f32_e32 v74, v74
	v_exp_f32_e32 v75, v75
	v_pk_mul_f32 v[70:71], v[70:71], v[150:151] op_sel_hi:[1,0]
	v_pk_mul_f32 v[66:67], v[66:67], v[150:151] op_sel_hi:[1,0]
	v_pk_add_f32 v[74:75], v[74:75], 1.0 op_sel_hi:[1,0]
	v_mul_f32_e32 v66, 0xbfb8aa3b, v66
	v_mul_f32_e32 v67, 0xbfb8aa3b, v67
	v_exp_f32_e32 v66, v66
	v_exp_f32_e32 v67, v67
	s_waitcnt vmcnt(1)
	v_lshlrev_b32_e32 v96, 16, v80
	v_and_b32_e32 v97, 0xffff0000, v80
	s_waitcnt vmcnt(0)
	v_lshlrev_b32_e32 v76, 16, v84
	v_and_b32_e32 v77, 0xffff0000, v84
	v_pk_add_f32 v[66:67], v[66:67], 1.0 op_sel_hi:[1,0]
	v_rcp_f32_e32 v73, v73
	v_rcp_f32_e32 v72, v72
	s_nop 0
	v_pk_fma_f32 v[72:73], v[72:73], v[96:97], v[76:77]
	v_pk_mul_f32 v[76:77], v[78:79], v[240:241] op_sel_hi:[1,0]
	v_exp_f32_e32 v76, v76
	v_exp_f32_e32 v77, v77
	v_lshlrev_b32_e32 v78, 16, v85
	v_and_b32_e32 v79, 0xffff0000, v85
	v_lshlrev_b32_e32 v80, 16, v81
	v_pk_add_f32 v[76:77], v[76:77], 1.0 op_sel_hi:[1,0]
	v_and_b32_e32 v81, 0xffff0000, v81
	v_rcp_f32_e32 v77, v77
	v_rcp_f32_e32 v76, v76
	s_nop 0
	v_pk_fma_f32 v[78:79], v[76:77], v[80:81], v[78:79]
	v_pk_mul_f32 v[76:77], v[94:95], v[240:241] op_sel_hi:[1,0]
	v_exp_f32_e32 v76, v76
	v_exp_f32_e32 v77, v77
	v_lshlrev_b32_e32 v84, 16, v82
	v_and_b32_e32 v85, 0xffff0000, v82
	v_lshlrev_b32_e32 v80, 16, v86
	v_pk_add_f32 v[76:77], v[76:77], 1.0 op_sel_hi:[1,0]
	v_and_b32_e32 v81, 0xffff0000, v86
	v_rcp_f32_e32 v77, v77
	v_rcp_f32_e32 v76, v76
	s_nop 0
	v_pk_fma_f32 v[84:85], v[76:77], v[84:85], v[80:81]
	v_lshlrev_b32_e32 v80, 16, v83
	v_and_b32_e32 v81, 0xffff0000, v83
	v_lshlrev_b32_e32 v76, 16, v87
	v_and_b32_e32 v77, 0xffff0000, v87
	v_rcp_f32_e32 v75, v75
	v_rcp_f32_e32 v74, v74
	s_nop 0
	v_pk_fma_f32 v[86:87], v[74:75], v[80:81], v[76:77]
	v_cvt_pk_bf16_f32 v74, v72, v73
	v_cvt_pk_bf16_f32 v75, v78, v79
	v_cvt_pk_bf16_f32 v76, v84, v85
	v_cvt_pk_bf16_f32 v77, v86, v87
	global_store_dwordx4 v[90:91], v[74:77], off
	v_pk_mul_f32 v[80:81], v[72:73], v[72:73]
	v_pk_mul_f32 v[82:83], v[78:79], v[78:79]
	global_load_dwordx4 v[72:75], v[90:91], off offset:256
	global_load_dwordx4 v[76:79], v[92:93], off offset:256
	v_pk_mul_f32 v[92:93], v[64:65], v[150:151] op_sel_hi:[1,0]
	v_pk_mul_f32 v[64:65], v[68:69], v[240:241] op_sel_hi:[1,0]
	v_exp_f32_e32 v64, v64
	v_exp_f32_e32 v65, v65
	v_pk_mul_f32 v[84:85], v[84:85], v[84:85]
	v_pk_mul_f32 v[86:87], v[86:87], v[86:87]
	v_pk_add_f32 v[64:65], v[64:65], 1.0 op_sel_hi:[1,0]
	s_waitcnt vmcnt(1)
	v_lshlrev_b32_e32 v94, 16, v72
	v_and_b32_e32 v95, 0xffff0000, v72
	s_waitcnt vmcnt(0)
	v_lshlrev_b32_e32 v68, 16, v76
	v_and_b32_e32 v69, 0xffff0000, v76
	v_rcp_f32_e32 v65, v65
	v_rcp_f32_e32 v64, v64
	s_nop 0
	v_pk_fma_f32 v[64:65], v[64:65], v[94:95], v[68:69]
	v_pk_mul_f32 v[68:69], v[70:71], v[240:241] op_sel_hi:[1,0]
	v_exp_f32_e32 v68, v68
	v_exp_f32_e32 v69, v69
	v_lshlrev_b32_e32 v70, 16, v77
	v_and_b32_e32 v71, 0xffff0000, v77
	v_lshlrev_b32_e32 v72, 16, v73
	v_pk_add_f32 v[68:69], v[68:69], 1.0 op_sel_hi:[1,0]
	v_and_b32_e32 v73, 0xffff0000, v73
	v_rcp_f32_e32 v69, v69
	v_rcp_f32_e32 v68, v68
	s_nop 0
	v_pk_fma_f32 v[68:69], v[68:69], v[72:73], v[70:71]
	v_pk_mul_f32 v[70:71], v[92:93], v[240:241] op_sel_hi:[1,0]
	v_exp_f32_e32 v70, v70
	v_exp_f32_e32 v71, v71
	v_lshlrev_b32_e32 v76, 16, v74
	v_and_b32_e32 v77, 0xffff0000, v74
	v_lshlrev_b32_e32 v72, 16, v78
	v_pk_add_f32 v[70:71], v[70:71], 1.0 op_sel_hi:[1,0]
	v_and_b32_e32 v73, 0xffff0000, v78
	v_rcp_f32_e32 v71, v71
	v_rcp_f32_e32 v70, v70
	s_nop 0
	v_pk_fma_f32 v[76:77], v[70:71], v[76:77], v[72:73]
	v_lshlrev_b32_e32 v72, 16, v75
	v_and_b32_e32 v73, 0xffff0000, v75
	v_lshlrev_b32_e32 v70, 16, v79
	v_and_b32_e32 v71, 0xffff0000, v79
	v_rcp_f32_e32 v67, v67
	v_rcp_f32_e32 v66, v66
	s_nop 0
	v_pk_fma_f32 v[66:67], v[66:67], v[72:73], v[70:71]
	v_cvt_pk_bf16_f32 v70, v64, v65
	v_cvt_pk_bf16_f32 v71, v68, v69
	v_cvt_pk_bf16_f32 v72, v76, v77
	v_cvt_pk_bf16_f32 v73, v66, v67
	global_store_dwordx4 v[90:91], v[70:73], off offset:256
	v_pk_mul_f32 v[66:67], v[66:67], v[66:67]
	v_pk_mul_f32 v[64:65], v[64:65], v[64:65]
	v_pk_mul_f32 v[70:71], v[76:77], v[76:77]
	v_pk_mul_f32 v[68:69], v[68:69], v[68:69]
	v_add_f32_e32 v72, v86, v87
	v_add_f32_e32 v73, v84, v85
	v_add_f32_e32 v66, v66, v67
	v_add_f32_e32 v67, v70, v71
	v_add_f32_e32 v72, v73, v72
	v_add_f32_e32 v73, v82, v83
	v_add_f32_e32 v74, v80, v81
	v_add_f32_e32 v66, v67, v66
	v_add_f32_e32 v67, v68, v69
	v_add_f32_e32 v64, v64, v65
	v_add_f32_e32 v73, v74, v73
	v_add_f32_e32 v64, v64, v67
	v_add_f32_e32 v72, v73, v72
	v_add_f32_e32 v64, v64, v66
	v_add_f32_e32 v64, v72, v64
	ds_bpermute_b32 v65, v169, v64
	s_waitcnt lgkmcnt(0)
	v_add_f32_e32 v64, v64, v65
	ds_bpermute_b32 v65, v155, v64
	s_and_saveexec_b64 s[0:1], s[46:47]
	s_cbranch_execz .LBB0_478
	s_waitcnt lgkmcnt(0)
	v_add_f32_e32 v66, v64, v65
	v_lshlrev_b64 v[64:65], 6, v[88:89]
	v_lshl_add_u64 v[64:65], s[6:7], 0, v[64:65]
	v_lshl_add_u64 v[64:65], s[42:43], 2, v[64:65]
	s_lshl_b32 s94, s35, 2
	v_lshl_add_u64 v[64:65], v[64:65], 0, s[94:95]
	global_store_dword v[64:65], v66, off
; DI unsigned pk2(float lo, float hi) { const f32x2_t v = {lo, hi}; const bf16x2_t b = __builtin_convertvector(v, bf16x2_t); return __builtin_bit_cast(unsigned, b); }
; DI float lo16(unsigned w) { return __uint_as_float(w << 16); }
; DI float hi16(unsigned w) { return __uint_as_float(w & 0xffff0000u); }
;     DI void operator()(const pg8::f32x4 (&acc)[2][2][4][2], const pg8::Unit& u, int wr, int wc, int fr, int fq) const {
;     ...
;                 for (int bj = 0; bj < 2; ++bj) { const size_t off = (size_t)row * 1024 + col0 + bj * 128;
;                     const u32x4 tw = *(const u32x4*)(T + off); const u32x4 xw = *(const u32x4*)(xr + off);
;                     const pg8::f32x4 a0 = acc[ai][bj][m][0] * r, a1 = acc[ai][bj][m][1] * r;
;                     const float o0 = lo16(xw.x) + lo16(tw.x) * __frcp_rn(1.0f + __expf(-a0[0])), o1 = hi16(xw.x) + hi16(tw.x) * __frcp_rn(1.0f + __expf(-a0[1]));
;                     const float o2 = lo16(xw.y) + lo16(tw.y) * __frcp_rn(1.0f + __expf(-a0[2])), o3 = hi16(xw.y) + hi16(tw.y) * __frcp_rn(1.0f + __expf(-a0[3]));
;                     const float o4 = lo16(xw.z) + lo16(tw.z) * __frcp_rn(1.0f + __expf(-a1[0])), o5 = hi16(xw.z) + hi16(tw.z) * __frcp_rn(1.0f + __expf(-a1[1]));
;                     const float o6 = lo16(xw.w) + lo16(tw.w) * __frcp_rn(1.0f + __expf(-a1[2])), o7 = hi16(xw.w) + hi16(tw.w) * __frcp_rn(1.0f + __expf(-a1[3]));
;                     u32x4 w; w.x = pk2(o0, o1); w.y = pk2(o2, o3); w.z = pk2(o4, o5); w.w = pk2(o6, o7); *(u32x4*)(xbo + off) = w;
;                     part += ((o0 * o0 + o1 * o1) + (o2 * o2 + o3 * o3)) + ((o4 * o4 + o5 * o5) + (o6 * o6 + o7 * o7)); }
;                 part += __shfl_xor(part, 16); part += __shfl_xor(part, 32);
;                 if (ssout && fq == 0) ssout[(size_t)row * 16 + u.pn * 4 + wc] = part;
.LBB0_478:
	s_or_b64 exec, exec, s[0:1]
	v_add_u32_e32 v72, 0x80, v142
	v_ashrrev_i32_e32 v73, 31, v72
	s_waitcnt lgkmcnt(0)
	v_lshlrev_b64 v[64:65], 10, v[72:73]
	v_lshl_add_u64 v[64:65], v[64:65], 0, v[140:141]
	v_lshlrev_b64 v[68:69], 1, v[64:65]
	v_lshl_add_u64 v[74:75], s[18:19], 0, v[68:69]
	global_load_dwordx4 v[64:67], v[74:75], off
	v_lshl_add_u64 v[76:77], s[12:13], 0, v[68:69]
	global_load_dwordx4 v[68:71], v[76:77], off
	v_pk_mul_f32 v[60:61], v[60:61], v[148:149] op_sel_hi:[1,0]
	v_pk_mul_f32 v[78:79], v[56:57], v[148:149] op_sel_hi:[1,0]
	v_pk_mul_f32 v[56:57], v[60:61], v[240:241] op_sel_hi:[1,0]
	v_exp_f32_e32 v56, v56
	v_exp_f32_e32 v57, v57
	v_pk_mul_f32 v[62:63], v[62:63], v[148:149] op_sel_hi:[1,0]
	v_pk_mul_f32 v[58:59], v[58:59], v[148:149] op_sel_hi:[1,0]
	v_pk_mul_f32 v[52:53], v[52:53], v[148:149] op_sel_hi:[1,0]
	v_pk_add_f32 v[56:57], v[56:57], 1.0 op_sel_hi:[1,0]
	v_mul_f32_e32 v58, 0xbfb8aa3b, v58
	v_mul_f32_e32 v59, 0xbfb8aa3b, v59
	v_exp_f32_e32 v58, v58
	v_exp_f32_e32 v59, v59
	v_pk_mul_f32 v[54:55], v[54:55], v[148:149] op_sel_hi:[1,0]
	v_pk_mul_f32 v[50:51], v[50:51], v[148:149] op_sel_hi:[1,0]
	v_pk_add_f32 v[58:59], v[58:59], 1.0 op_sel_hi:[1,0]
	v_mul_f32_e32 v50, 0xbfb8aa3b, v50
	v_mul_f32_e32 v51, 0xbfb8aa3b, v51
	v_exp_f32_e32 v50, v50
	v_exp_f32_e32 v51, v51
	s_waitcnt vmcnt(1)
	v_lshlrev_b32_e32 v80, 16, v64
	v_and_b32_e32 v81, 0xffff0000, v64
	s_waitcnt vmcnt(0)
	v_lshlrev_b32_e32 v60, 16, v68
	v_and_b32_e32 v61, 0xffff0000, v68
	v_pk_add_f32 v[50:51], v[50:51], 1.0 op_sel_hi:[1,0]
	v_rcp_f32_e32 v57, v57
	v_rcp_f32_e32 v56, v56
	s_nop 0
	v_pk_fma_f32 v[56:57], v[56:57], v[80:81], v[60:61]
	v_pk_mul_f32 v[60:61], v[62:63], v[240:241] op_sel_hi:[1,0]
	v_exp_f32_e32 v60, v60
	v_exp_f32_e32 v61, v61
	v_lshlrev_b32_e32 v62, 16, v69
	v_and_b32_e32 v63, 0xffff0000, v69
	v_lshlrev_b32_e32 v64, 16, v65
	v_pk_add_f32 v[60:61], v[60:61], 1.0 op_sel_hi:[1,0]
	v_and_b32_e32 v65, 0xffff0000, v65
	v_rcp_f32_e32 v61, v61
	v_rcp_f32_e32 v60, v60
	s_nop 0
	v_pk_fma_f32 v[62:63], v[60:61], v[64:65], v[62:63]
	v_pk_mul_f32 v[60:61], v[78:79], v[240:241] op_sel_hi:[1,0]
	v_exp_f32_e32 v60, v60
	v_exp_f32_e32 v61, v61
	v_lshlrev_b32_e32 v68, 16, v66
	v_and_b32_e32 v69, 0xffff0000, v66
	v_lshlrev_b32_e32 v64, 16, v70
	v_pk_add_f32 v[60:61], v[60:61], 1.0 op_sel_hi:[1,0]
	v_and_b32_e32 v65, 0xffff0000, v70
	v_rcp_f32_e32 v61, v61
	v_rcp_f32_e32 v60, v60
	s_nop 0
	v_pk_fma_f32 v[68:69], v[60:61], v[68:69], v[64:65]
	v_lshlrev_b32_e32 v64, 16, v67
	v_and_b32_e32 v65, 0xffff0000, v67
	v_lshlrev_b32_e32 v60, 16, v71
	v_and_b32_e32 v61, 0xffff0000, v71
	v_rcp_f32_e32 v59, v59
	v_rcp_f32_e32 v58, v58
	s_nop 0
	v_pk_fma_f32 v[70:71], v[58:59], v[64:65], v[60:61]
	v_cvt_pk_bf16_f32 v58, v56, v57
	v_cvt_pk_bf16_f32 v59, v62, v63
	v_cvt_pk_bf16_f32 v60, v68, v69
	v_cvt_pk_bf16_f32 v61, v70, v71
	global_store_dwordx4 v[74:75], v[58:61], off
	v_pk_mul_f32 v[64:65], v[56:57], v[56:57]
	v_pk_mul_f32 v[66:67], v[62:63], v[62:63]
	global_load_dwordx4 v[56:59], v[74:75], off offset:256
	global_load_dwordx4 v[60:63], v[76:77], off offset:256
	v_pk_mul_f32 v[76:77], v[48:49], v[148:149] op_sel_hi:[1,0]
	v_pk_mul_f32 v[48:49], v[52:53], v[240:241] op_sel_hi:[1,0]
	v_exp_f32_e32 v48, v48
	v_exp_f32_e32 v49, v49
	v_pk_mul_f32 v[68:69], v[68:69], v[68:69]
	v_pk_mul_f32 v[70:71], v[70:71], v[70:71]
	v_pk_add_f32 v[48:49], v[48:49], 1.0 op_sel_hi:[1,0]
	s_waitcnt vmcnt(1)
	v_lshlrev_b32_e32 v78, 16, v56
	v_and_b32_e32 v79, 0xffff0000, v56
	s_waitcnt vmcnt(0)
	v_lshlrev_b32_e32 v52, 16, v60
	v_and_b32_e32 v53, 0xffff0000, v60
	v_rcp_f32_e32 v49, v49
	v_rcp_f32_e32 v48, v48
	s_nop 0
	v_pk_fma_f32 v[48:49], v[48:49], v[78:79], v[52:53]
	v_pk_mul_f32 v[52:53], v[54:55], v[240:241] op_sel_hi:[1,0]
	v_exp_f32_e32 v52, v52
	v_exp_f32_e32 v53, v53
	v_lshlrev_b32_e32 v54, 16, v61
	v_and_b32_e32 v55, 0xffff0000, v61
	v_lshlrev_b32_e32 v56, 16, v57
	v_pk_add_f32 v[52:53], v[52:53], 1.0 op_sel_hi:[1,0]
	v_and_b32_e32 v57, 0xffff0000, v57
	v_rcp_f32_e32 v53, v53
	v_rcp_f32_e32 v52, v52
	s_nop 0
	v_pk_fma_f32 v[52:53], v[52:53], v[56:57], v[54:55]
	v_pk_mul_f32 v[54:55], v[76:77], v[240:241] op_sel_hi:[1,0]
	v_exp_f32_e32 v54, v54
	v_exp_f32_e32 v55, v55
	v_lshlrev_b32_e32 v60, 16, v58
	v_and_b32_e32 v61, 0xffff0000, v58
	v_lshlrev_b32_e32 v56, 16, v62
	v_pk_add_f32 v[54:55], v[54:55], 1.0 op_sel_hi:[1,0]
	v_and_b32_e32 v57, 0xffff0000, v62
	v_rcp_f32_e32 v55, v55
	v_rcp_f32_e32 v54, v54
	s_nop 0
	v_pk_fma_f32 v[60:61], v[54:55], v[60:61], v[56:57]
	v_lshlrev_b32_e32 v56, 16, v59
	v_and_b32_e32 v57, 0xffff0000, v59
	v_lshlrev_b32_e32 v54, 16, v63
	v_and_b32_e32 v55, 0xffff0000, v63
	v_rcp_f32_e32 v51, v51
	v_rcp_f32_e32 v50, v50
	s_nop 0
	v_pk_fma_f32 v[50:51], v[50:51], v[56:57], v[54:55]
	v_cvt_pk_bf16_f32 v54, v48, v49
	v_cvt_pk_bf16_f32 v55, v52, v53
	v_cvt_pk_bf16_f32 v56, v60, v61
	v_cvt_pk_bf16_f32 v57, v50, v51
	global_store_dwordx4 v[74:75], v[54:57], off offset:256
	v_pk_mul_f32 v[50:51], v[50:51], v[50:51]
	v_pk_mul_f32 v[48:49], v[48:49], v[48:49]
	v_pk_mul_f32 v[54:55], v[60:61], v[60:61]
	v_pk_mul_f32 v[52:53], v[52:53], v[52:53]
	v_add_f32_e32 v56, v70, v71
	v_add_f32_e32 v57, v68, v69
	v_add_f32_e32 v50, v50, v51
	v_add_f32_e32 v51, v54, v55
	v_add_f32_e32 v56, v57, v56
	v_add_f32_e32 v57, v66, v67
	v_add_f32_e32 v58, v64, v65
	v_add_f32_e32 v50, v51, v50
	v_add_f32_e32 v51, v52, v53
	v_add_f32_e32 v48, v48, v49
	v_add_f32_e32 v57, v58, v57
	v_add_f32_e32 v48, v48, v51
	v_add_f32_e32 v56, v57, v56
	v_add_f32_e32 v48, v48, v50
	v_add_f32_e32 v48, v56, v48
	ds_bpermute_b32 v49, v169, v48
	s_waitcnt lgkmcnt(0)
	v_add_f32_e32 v48, v48, v49
	ds_bpermute_b32 v49, v155, v48
	s_and_saveexec_b64 s[0:1], s[46:47]
	s_cbranch_execz .LBB0_480
	s_waitcnt lgkmcnt(0)
	v_add_f32_e32 v50, v48, v49
	v_lshlrev_b64 v[48:49], 6, v[72:73]
	v_lshl_add_u64 v[48:49], s[6:7], 0, v[48:49]
	v_lshl_add_u64 v[48:49], s[42:43], 2, v[48:49]
	s_lshl_b32 s94, s35, 2
	v_lshl_add_u64 v[48:49], v[48:49], 0, s[94:95]
	global_store_dword v[48:49], v50, off
; DI unsigned pk2(float lo, float hi) { const f32x2_t v = {lo, hi}; const bf16x2_t b = __builtin_convertvector(v, bf16x2_t); return __builtin_bit_cast(unsigned, b); }
; DI float lo16(unsigned w) { return __uint_as_float(w << 16); }
; DI float hi16(unsigned w) { return __uint_as_float(w & 0xffff0000u); }
;     DI void operator()(const pg8::f32x4 (&acc)[2][2][4][2], const pg8::Unit& u, int wr, int wc, int fr, int fq) const {
;     ...
;                 for (int bj = 0; bj < 2; ++bj) { const size_t off = (size_t)row * 1024 + col0 + bj * 128;
;                     const u32x4 tw = *(const u32x4*)(T + off); const u32x4 xw = *(const u32x4*)(xr + off);
;                     const pg8::f32x4 a0 = acc[ai][bj][m][0] * r, a1 = acc[ai][bj][m][1] * r;
;                     const float o0 = lo16(xw.x) + lo16(tw.x) * __frcp_rn(1.0f + __expf(-a0[0])), o1 = hi16(xw.x) + hi16(tw.x) * __frcp_rn(1.0f + __expf(-a0[1]));
;                     const float o2 = lo16(xw.y) + lo16(tw.y) * __frcp_rn(1.0f + __expf(-a0[2])), o3 = hi16(xw.y) + hi16(tw.y) * __frcp_rn(1.0f + __expf(-a0[3]));
;                     const float o4 = lo16(xw.z) + lo16(tw.z) * __frcp_rn(1.0f + __expf(-a1[0])), o5 = hi16(xw.z) + hi16(tw.z) * __frcp_rn(1.0f + __expf(-a1[1]));
;                     const float o6 = lo16(xw.w) + lo16(tw.w) * __frcp_rn(1.0f + __expf(-a1[2])), o7 = hi16(xw.w) + hi16(tw.w) * __frcp_rn(1.0f + __expf(-a1[3]));
;                     u32x4 w; w.x = pk2(o0, o1); w.y = pk2(o2, o3); w.z = pk2(o4, o5); w.w = pk2(o6, o7); *(u32x4*)(xbo + off) = w;
;                     part += ((o0 * o0 + o1 * o1) + (o2 * o2 + o3 * o3)) + ((o4 * o4 + o5 * o5) + (o6 * o6 + o7 * o7)); }
;                 part += __shfl_xor(part, 16); part += __shfl_xor(part, 32);
;                 if (ssout && fq == 0) ssout[(size_t)row * 16 + u.pn * 4 + wc] = part;
.LBB0_480:
	s_or_b64 exec, exec, s[0:1]
	v_add_u32_e32 v56, 0x90, v142
	v_ashrrev_i32_e32 v57, 31, v56
	s_waitcnt lgkmcnt(0)
	v_lshlrev_b64 v[48:49], 10, v[56:57]
	v_lshl_add_u64 v[48:49], v[48:49], 0, v[140:141]
	v_lshlrev_b64 v[52:53], 1, v[48:49]
	v_lshl_add_u64 v[58:59], s[18:19], 0, v[52:53]
	global_load_dwordx4 v[48:51], v[58:59], off
	v_lshl_add_u64 v[60:61], s[12:13], 0, v[52:53]
	global_load_dwordx4 v[52:55], v[60:61], off
	v_pk_mul_f32 v[44:45], v[44:45], v[146:147] op_sel_hi:[1,0]
	v_pk_mul_f32 v[62:63], v[40:41], v[146:147] op_sel_hi:[1,0]
	v_pk_mul_f32 v[40:41], v[44:45], v[240:241] op_sel_hi:[1,0]
	v_exp_f32_e32 v40, v40
	v_exp_f32_e32 v41, v41
	v_pk_mul_f32 v[46:47], v[46:47], v[146:147] op_sel_hi:[1,0]
	v_pk_mul_f32 v[42:43], v[42:43], v[146:147] op_sel_hi:[1,0]
	v_pk_mul_f32 v[36:37], v[36:37], v[146:147] op_sel_hi:[1,0]
	v_pk_add_f32 v[40:41], v[40:41], 1.0 op_sel_hi:[1,0]
	v_mul_f32_e32 v42, 0xbfb8aa3b, v42
	v_mul_f32_e32 v43, 0xbfb8aa3b, v43
	v_exp_f32_e32 v42, v42
	v_exp_f32_e32 v43, v43
	v_pk_mul_f32 v[38:39], v[38:39], v[146:147] op_sel_hi:[1,0]
	v_pk_mul_f32 v[34:35], v[34:35], v[146:147] op_sel_hi:[1,0]
	v_pk_add_f32 v[42:43], v[42:43], 1.0 op_sel_hi:[1,0]
	v_mul_f32_e32 v34, 0xbfb8aa3b, v34
	v_mul_f32_e32 v35, 0xbfb8aa3b, v35
	v_exp_f32_e32 v34, v34
	v_exp_f32_e32 v35, v35
	s_waitcnt vmcnt(1)
	v_lshlrev_b32_e32 v64, 16, v48
	v_and_b32_e32 v65, 0xffff0000, v48
	s_waitcnt vmcnt(0)
	v_lshlrev_b32_e32 v44, 16, v52
	v_and_b32_e32 v45, 0xffff0000, v52
	v_pk_add_f32 v[34:35], v[34:35], 1.0 op_sel_hi:[1,0]
	v_rcp_f32_e32 v41, v41
	v_rcp_f32_e32 v40, v40
	s_nop 0
	v_pk_fma_f32 v[40:41], v[40:41], v[64:65], v[44:45]
	v_pk_mul_f32 v[44:45], v[46:47], v[240:241] op_sel_hi:[1,0]
	v_exp_f32_e32 v44, v44
	v_exp_f32_e32 v45, v45
	v_lshlrev_b32_e32 v46, 16, v53
	v_and_b32_e32 v47, 0xffff0000, v53
	v_lshlrev_b32_e32 v48, 16, v49
	v_pk_add_f32 v[44:45], v[44:45], 1.0 op_sel_hi:[1,0]
	v_and_b32_e32 v49, 0xffff0000, v49
	v_rcp_f32_e32 v45, v45
	v_rcp_f32_e32 v44, v44
	s_nop 0
	v_pk_fma_f32 v[46:47], v[44:45], v[48:49], v[46:47]
	v_pk_mul_f32 v[44:45], v[62:63], v[240:241] op_sel_hi:[1,0]
	v_exp_f32_e32 v44, v44
	v_exp_f32_e32 v45, v45
	v_lshlrev_b32_e32 v52, 16, v50
	v_and_b32_e32 v53, 0xffff0000, v50
	v_lshlrev_b32_e32 v48, 16, v54
	v_pk_add_f32 v[44:45], v[44:45], 1.0 op_sel_hi:[1,0]
	v_and_b32_e32 v49, 0xffff0000, v54
	v_rcp_f32_e32 v45, v45
	v_rcp_f32_e32 v44, v44
	s_nop 0
	v_pk_fma_f32 v[52:53], v[44:45], v[52:53], v[48:49]
	v_lshlrev_b32_e32 v48, 16, v51
	v_and_b32_e32 v49, 0xffff0000, v51
	v_lshlrev_b32_e32 v44, 16, v55
	v_and_b32_e32 v45, 0xffff0000, v55
	v_rcp_f32_e32 v43, v43
	v_rcp_f32_e32 v42, v42
	s_nop 0
	v_pk_fma_f32 v[54:55], v[42:43], v[48:49], v[44:45]
	v_cvt_pk_bf16_f32 v42, v40, v41
	v_cvt_pk_bf16_f32 v43, v46, v47
	v_cvt_pk_bf16_f32 v44, v52, v53
	v_cvt_pk_bf16_f32 v45, v54, v55
	global_store_dwordx4 v[58:59], v[42:45], off
	v_pk_mul_f32 v[48:49], v[40:41], v[40:41]
	v_pk_mul_f32 v[50:51], v[46:47], v[46:47]
	global_load_dwordx4 v[40:43], v[58:59], off offset:256
	global_load_dwordx4 v[44:47], v[60:61], off offset:256
	v_pk_mul_f32 v[60:61], v[32:33], v[146:147] op_sel_hi:[1,0]
	v_pk_mul_f32 v[32:33], v[36:37], v[240:241] op_sel_hi:[1,0]
	v_exp_f32_e32 v32, v32
	v_exp_f32_e32 v33, v33
	v_pk_mul_f32 v[52:53], v[52:53], v[52:53]
	v_pk_mul_f32 v[54:55], v[54:55], v[54:55]
	v_pk_add_f32 v[32:33], v[32:33], 1.0 op_sel_hi:[1,0]
	s_waitcnt vmcnt(1)
	v_lshlrev_b32_e32 v62, 16, v40
	v_and_b32_e32 v63, 0xffff0000, v40
	s_waitcnt vmcnt(0)
	v_lshlrev_b32_e32 v36, 16, v44
	v_and_b32_e32 v37, 0xffff0000, v44
	v_rcp_f32_e32 v33, v33
	v_rcp_f32_e32 v32, v32
	s_nop 0
	v_pk_fma_f32 v[32:33], v[32:33], v[62:63], v[36:37]
	v_pk_mul_f32 v[36:37], v[38:39], v[240:241] op_sel_hi:[1,0]
	v_exp_f32_e32 v36, v36
	v_exp_f32_e32 v37, v37
	v_lshlrev_b32_e32 v38, 16, v45
	v_and_b32_e32 v39, 0xffff0000, v45
	v_lshlrev_b32_e32 v40, 16, v41
	v_pk_add_f32 v[36:37], v[36:37], 1.0 op_sel_hi:[1,0]
	v_and_b32_e32 v41, 0xffff0000, v41
	v_rcp_f32_e32 v37, v37
	v_rcp_f32_e32 v36, v36
	s_nop 0
	v_pk_fma_f32 v[36:37], v[36:37], v[40:41], v[38:39]
	v_pk_mul_f32 v[38:39], v[60:61], v[240:241] op_sel_hi:[1,0]
	v_exp_f32_e32 v38, v38
	v_exp_f32_e32 v39, v39
	v_lshlrev_b32_e32 v44, 16, v42
	v_and_b32_e32 v45, 0xffff0000, v42
	v_lshlrev_b32_e32 v40, 16, v46
	v_pk_add_f32 v[38:39], v[38:39], 1.0 op_sel_hi:[1,0]
	v_and_b32_e32 v41, 0xffff0000, v46
	v_rcp_f32_e32 v39, v39
	v_rcp_f32_e32 v38, v38
	s_nop 0
	v_pk_fma_f32 v[44:45], v[38:39], v[44:45], v[40:41]
	v_lshlrev_b32_e32 v40, 16, v43
	v_and_b32_e32 v41, 0xffff0000, v43
	v_lshlrev_b32_e32 v38, 16, v47
	v_and_b32_e32 v39, 0xffff0000, v47
	v_rcp_f32_e32 v35, v35
	v_rcp_f32_e32 v34, v34
	s_nop 0
	v_pk_fma_f32 v[34:35], v[34:35], v[40:41], v[38:39]
	v_cvt_pk_bf16_f32 v38, v32, v33
	v_cvt_pk_bf16_f32 v39, v36, v37
	v_cvt_pk_bf16_f32 v40, v44, v45
	v_cvt_pk_bf16_f32 v41, v34, v35
	global_store_dwordx4 v[58:59], v[38:41], off offset:256
	v_pk_mul_f32 v[34:35], v[34:35], v[34:35]
	v_pk_mul_f32 v[32:33], v[32:33], v[32:33]
	v_pk_mul_f32 v[38:39], v[44:45], v[44:45]
	v_pk_mul_f32 v[36:37], v[36:37], v[36:37]
	v_add_f32_e32 v40, v54, v55
	v_add_f32_e32 v41, v52, v53
	v_add_f32_e32 v34, v34, v35
	v_add_f32_e32 v35, v38, v39
	v_add_f32_e32 v40, v41, v40
	v_add_f32_e32 v41, v50, v51
	v_add_f32_e32 v42, v48, v49
	v_add_f32_e32 v34, v35, v34
	v_add_f32_e32 v35, v36, v37
	v_add_f32_e32 v32, v32, v33
	v_add_f32_e32 v41, v42, v41
	v_add_f32_e32 v32, v32, v35
	v_add_f32_e32 v40, v41, v40
	v_add_f32_e32 v32, v32, v34
	v_add_f32_e32 v32, v40, v32
	ds_bpermute_b32 v33, v169, v32
	s_waitcnt lgkmcnt(0)
	v_add_f32_e32 v32, v32, v33
	ds_bpermute_b32 v33, v155, v32
	s_and_saveexec_b64 s[0:1], s[46:47]
	s_cbranch_execz .LBB0_482
	s_waitcnt lgkmcnt(0)
	v_add_f32_e32 v34, v32, v33
	v_lshlrev_b64 v[32:33], 6, v[56:57]
	v_lshl_add_u64 v[32:33], s[6:7], 0, v[32:33]
	v_lshl_add_u64 v[32:33], s[42:43], 2, v[32:33]
	s_lshl_b32 s94, s35, 2
	v_lshl_add_u64 v[32:33], v[32:33], 0, s[94:95]
	global_store_dword v[32:33], v34, off
; DI unsigned pk2(float lo, float hi) { const f32x2_t v = {lo, hi}; const bf16x2_t b = __builtin_convertvector(v, bf16x2_t); return __builtin_bit_cast(unsigned, b); }
; DI float lo16(unsigned w) { return __uint_as_float(w << 16); }
; DI float hi16(unsigned w) { return __uint_as_float(w & 0xffff0000u); }
;     DI void operator()(const pg8::f32x4 (&acc)[2][2][4][2], const pg8::Unit& u, int wr, int wc, int fr, int fq) const {
;     ...
;                 for (int bj = 0; bj < 2; ++bj) { const size_t off = (size_t)row * 1024 + col0 + bj * 128;
;                     const u32x4 tw = *(const u32x4*)(T + off); const u32x4 xw = *(const u32x4*)(xr + off);
;                     const pg8::f32x4 a0 = acc[ai][bj][m][0] * r, a1 = acc[ai][bj][m][1] * r;
;                     const float o0 = lo16(xw.x) + lo16(tw.x) * __frcp_rn(1.0f + __expf(-a0[0])), o1 = hi16(xw.x) + hi16(tw.x) * __frcp_rn(1.0f + __expf(-a0[1]));
;                     const float o2 = lo16(xw.y) + lo16(tw.y) * __frcp_rn(1.0f + __expf(-a0[2])), o3 = hi16(xw.y) + hi16(tw.y) * __frcp_rn(1.0f + __expf(-a0[3]));
;                     const float o4 = lo16(xw.z) + lo16(tw.z) * __frcp_rn(1.0f + __expf(-a1[0])), o5 = hi16(xw.z) + hi16(tw.z) * __frcp_rn(1.0f + __expf(-a1[1]));
;                     const float o6 = lo16(xw.w) + lo16(tw.w) * __frcp_rn(1.0f + __expf(-a1[2])), o7 = hi16(xw.w) + hi16(tw.w) * __frcp_rn(1.0f + __expf(-a1[3]));
;                     u32x4 w; w.x = pk2(o0, o1); w.y = pk2(o2, o3); w.z = pk2(o4, o5); w.w = pk2(o6, o7); *(u32x4*)(xbo + off) = w;
;                     part += ((o0 * o0 + o1 * o1) + (o2 * o2 + o3 * o3)) + ((o4 * o4 + o5 * o5) + (o6 * o6 + o7 * o7)); }
;                 part += __shfl_xor(part, 16); part += __shfl_xor(part, 32);
;                 if (ssout && fq == 0) ssout[(size_t)row * 16 + u.pn * 4 + wc] = part;
.LBB0_482:
	s_or_b64 exec, exec, s[0:1]
	v_add_u32_e32 v40, 0xa0, v142
	v_ashrrev_i32_e32 v41, 31, v40
	s_waitcnt lgkmcnt(0)
	v_lshlrev_b64 v[32:33], 10, v[40:41]
	v_lshl_add_u64 v[32:33], v[32:33], 0, v[140:141]
	v_lshlrev_b64 v[36:37], 1, v[32:33]
	v_lshl_add_u64 v[42:43], s[18:19], 0, v[36:37]
	global_load_dwordx4 v[32:35], v[42:43], off
	v_lshl_add_u64 v[44:45], s[12:13], 0, v[36:37]
	global_load_dwordx4 v[36:39], v[44:45], off
	v_pk_mul_f32 v[28:29], v[28:29], v[144:145] op_sel_hi:[1,0]
	v_pk_mul_f32 v[46:47], v[24:25], v[144:145] op_sel_hi:[1,0]
	v_pk_mul_f32 v[24:25], v[28:29], v[240:241] op_sel_hi:[1,0]
	v_exp_f32_e32 v24, v24
	v_exp_f32_e32 v25, v25
	v_pk_mul_f32 v[30:31], v[30:31], v[144:145] op_sel_hi:[1,0]
	v_pk_mul_f32 v[26:27], v[26:27], v[144:145] op_sel_hi:[1,0]
	v_pk_mul_f32 v[20:21], v[20:21], v[144:145] op_sel_hi:[1,0]
	v_pk_add_f32 v[24:25], v[24:25], 1.0 op_sel_hi:[1,0]
	v_mul_f32_e32 v26, 0xbfb8aa3b, v26
	v_mul_f32_e32 v27, 0xbfb8aa3b, v27
	v_exp_f32_e32 v26, v26
	v_exp_f32_e32 v27, v27
	v_pk_mul_f32 v[22:23], v[22:23], v[144:145] op_sel_hi:[1,0]
	v_pk_mul_f32 v[18:19], v[18:19], v[144:145] op_sel_hi:[1,0]
	v_pk_add_f32 v[26:27], v[26:27], 1.0 op_sel_hi:[1,0]
	v_mul_f32_e32 v18, 0xbfb8aa3b, v18
	v_mul_f32_e32 v19, 0xbfb8aa3b, v19
	v_exp_f32_e32 v18, v18
	v_exp_f32_e32 v19, v19
	s_waitcnt vmcnt(1)
	v_lshlrev_b32_e32 v48, 16, v32
	v_and_b32_e32 v49, 0xffff0000, v32
	s_waitcnt vmcnt(0)
	v_lshlrev_b32_e32 v28, 16, v36
	v_and_b32_e32 v29, 0xffff0000, v36
	v_pk_add_f32 v[18:19], v[18:19], 1.0 op_sel_hi:[1,0]
	v_rcp_f32_e32 v25, v25
	v_rcp_f32_e32 v24, v24
	s_nop 0
	v_pk_fma_f32 v[24:25], v[24:25], v[48:49], v[28:29]
	v_pk_mul_f32 v[28:29], v[30:31], v[240:241] op_sel_hi:[1,0]
	v_exp_f32_e32 v28, v28
	v_exp_f32_e32 v29, v29
	v_lshlrev_b32_e32 v30, 16, v37
	v_and_b32_e32 v31, 0xffff0000, v37
	v_lshlrev_b32_e32 v32, 16, v33
	v_pk_add_f32 v[28:29], v[28:29], 1.0 op_sel_hi:[1,0]
	v_and_b32_e32 v33, 0xffff0000, v33
	v_rcp_f32_e32 v29, v29
	v_rcp_f32_e32 v28, v28
	s_nop 0
	v_pk_fma_f32 v[30:31], v[28:29], v[32:33], v[30:31]
	v_pk_mul_f32 v[28:29], v[46:47], v[240:241] op_sel_hi:[1,0]
	v_exp_f32_e32 v28, v28
	v_exp_f32_e32 v29, v29
	v_lshlrev_b32_e32 v36, 16, v34
	v_and_b32_e32 v37, 0xffff0000, v34
	v_lshlrev_b32_e32 v32, 16, v38
	v_pk_add_f32 v[28:29], v[28:29], 1.0 op_sel_hi:[1,0]
	v_and_b32_e32 v33, 0xffff0000, v38
	v_rcp_f32_e32 v29, v29
	v_rcp_f32_e32 v28, v28
	s_nop 0
	v_pk_fma_f32 v[36:37], v[28:29], v[36:37], v[32:33]
	v_lshlrev_b32_e32 v32, 16, v35
	v_and_b32_e32 v33, 0xffff0000, v35
	v_lshlrev_b32_e32 v28, 16, v39
	v_and_b32_e32 v29, 0xffff0000, v39
	v_rcp_f32_e32 v27, v27
	v_rcp_f32_e32 v26, v26
	s_nop 0
	v_pk_fma_f32 v[38:39], v[26:27], v[32:33], v[28:29]
	v_cvt_pk_bf16_f32 v26, v24, v25
	v_cvt_pk_bf16_f32 v27, v30, v31
	v_cvt_pk_bf16_f32 v28, v36, v37
	v_cvt_pk_bf16_f32 v29, v38, v39
	global_store_dwordx4 v[42:43], v[26:29], off
	v_pk_mul_f32 v[32:33], v[24:25], v[24:25]
	v_pk_mul_f32 v[34:35], v[30:31], v[30:31]
	global_load_dwordx4 v[24:27], v[42:43], off offset:256
	global_load_dwordx4 v[28:31], v[44:45], off offset:256
	v_pk_mul_f32 v[44:45], v[16:17], v[144:145] op_sel_hi:[1,0]
	v_pk_mul_f32 v[16:17], v[20:21], v[240:241] op_sel_hi:[1,0]
	v_exp_f32_e32 v16, v16
	v_exp_f32_e32 v17, v17
	v_pk_mul_f32 v[36:37], v[36:37], v[36:37]
	v_pk_mul_f32 v[38:39], v[38:39], v[38:39]
	v_pk_add_f32 v[16:17], v[16:17], 1.0 op_sel_hi:[1,0]
	s_waitcnt vmcnt(1)
	v_lshlrev_b32_e32 v46, 16, v24
	v_and_b32_e32 v47, 0xffff0000, v24
	s_waitcnt vmcnt(0)
	v_lshlrev_b32_e32 v20, 16, v28
	v_and_b32_e32 v21, 0xffff0000, v28
	v_rcp_f32_e32 v17, v17
	v_rcp_f32_e32 v16, v16
	s_nop 0
	v_pk_fma_f32 v[16:17], v[16:17], v[46:47], v[20:21]
	v_pk_mul_f32 v[20:21], v[22:23], v[240:241] op_sel_hi:[1,0]
	v_exp_f32_e32 v20, v20
	v_exp_f32_e32 v21, v21
	v_lshlrev_b32_e32 v22, 16, v29
	v_and_b32_e32 v23, 0xffff0000, v29
	v_lshlrev_b32_e32 v24, 16, v25
	v_pk_add_f32 v[20:21], v[20:21], 1.0 op_sel_hi:[1,0]
	v_and_b32_e32 v25, 0xffff0000, v25
	v_rcp_f32_e32 v21, v21
	v_rcp_f32_e32 v20, v20
	s_nop 0
	v_pk_fma_f32 v[20:21], v[20:21], v[24:25], v[22:23]
	v_pk_mul_f32 v[22:23], v[44:45], v[240:241] op_sel_hi:[1,0]
	v_exp_f32_e32 v22, v22
	v_exp_f32_e32 v23, v23
	v_lshlrev_b32_e32 v28, 16, v26
	v_and_b32_e32 v29, 0xffff0000, v26
	v_lshlrev_b32_e32 v24, 16, v30
	v_pk_add_f32 v[22:23], v[22:23], 1.0 op_sel_hi:[1,0]
	v_and_b32_e32 v25, 0xffff0000, v30
	v_rcp_f32_e32 v23, v23
	v_rcp_f32_e32 v22, v22
	s_nop 0
	v_pk_fma_f32 v[28:29], v[22:23], v[28:29], v[24:25]
	v_lshlrev_b32_e32 v24, 16, v27
	v_and_b32_e32 v25, 0xffff0000, v27
	v_lshlrev_b32_e32 v22, 16, v31
	v_and_b32_e32 v23, 0xffff0000, v31
	v_rcp_f32_e32 v19, v19
	v_rcp_f32_e32 v18, v18
	s_nop 0
	v_pk_fma_f32 v[18:19], v[18:19], v[24:25], v[22:23]
	v_cvt_pk_bf16_f32 v22, v16, v17
	v_cvt_pk_bf16_f32 v23, v20, v21
	v_cvt_pk_bf16_f32 v24, v28, v29
	v_cvt_pk_bf16_f32 v25, v18, v19
	global_store_dwordx4 v[42:43], v[22:25], off offset:256
	v_pk_mul_f32 v[18:19], v[18:19], v[18:19]
	v_pk_mul_f32 v[16:17], v[16:17], v[16:17]
	v_pk_mul_f32 v[22:23], v[28:29], v[28:29]
	v_pk_mul_f32 v[20:21], v[20:21], v[20:21]
	v_add_f32_e32 v24, v38, v39
	v_add_f32_e32 v25, v36, v37
	v_add_f32_e32 v18, v18, v19
	v_add_f32_e32 v19, v22, v23
	v_add_f32_e32 v24, v25, v24
	v_add_f32_e32 v25, v34, v35
	v_add_f32_e32 v26, v32, v33
	v_add_f32_e32 v18, v19, v18
	v_add_f32_e32 v19, v20, v21
	v_add_f32_e32 v16, v16, v17
	v_add_f32_e32 v25, v26, v25
	v_add_f32_e32 v16, v16, v19
	v_add_f32_e32 v24, v25, v24
	v_add_f32_e32 v16, v16, v18
	v_add_f32_e32 v16, v24, v16
	ds_bpermute_b32 v17, v169, v16
	s_waitcnt lgkmcnt(0)
	v_add_f32_e32 v16, v16, v17
	ds_bpermute_b32 v17, v155, v16
	s_and_saveexec_b64 s[0:1], s[46:47]
	s_cbranch_execz .LBB0_484
	s_waitcnt lgkmcnt(0)
	v_add_f32_e32 v18, v16, v17
	v_lshlrev_b64 v[16:17], 6, v[40:41]
	v_lshl_add_u64 v[16:17], s[6:7], 0, v[16:17]
	v_lshl_add_u64 v[16:17], s[42:43], 2, v[16:17]
	s_lshl_b32 s94, s35, 2
	v_lshl_add_u64 v[16:17], v[16:17], 0, s[94:95]
	global_store_dword v[16:17], v18, off
; DI unsigned pk2(float lo, float hi) { const f32x2_t v = {lo, hi}; const bf16x2_t b = __builtin_convertvector(v, bf16x2_t); return __builtin_bit_cast(unsigned, b); }
; DI float lo16(unsigned w) { return __uint_as_float(w << 16); }
; DI float hi16(unsigned w) { return __uint_as_float(w & 0xffff0000u); }
;     DI void operator()(const pg8::f32x4 (&acc)[2][2][4][2], const pg8::Unit& u, int wr, int wc, int fr, int fq) const {
;     ...
;                 for (int bj = 0; bj < 2; ++bj) { const size_t off = (size_t)row * 1024 + col0 + bj * 128;
;                     const u32x4 tw = *(const u32x4*)(T + off); const u32x4 xw = *(const u32x4*)(xr + off);
;                     const pg8::f32x4 a0 = acc[ai][bj][m][0] * r, a1 = acc[ai][bj][m][1] * r;
;                     const float o0 = lo16(xw.x) + lo16(tw.x) * __frcp_rn(1.0f + __expf(-a0[0])), o1 = hi16(xw.x) + hi16(tw.x) * __frcp_rn(1.0f + __expf(-a0[1]));
;                     const float o2 = lo16(xw.y) + lo16(tw.y) * __frcp_rn(1.0f + __expf(-a0[2])), o3 = hi16(xw.y) + hi16(tw.y) * __frcp_rn(1.0f + __expf(-a0[3]));
;                     const float o4 = lo16(xw.z) + lo16(tw.z) * __frcp_rn(1.0f + __expf(-a1[0])), o5 = hi16(xw.z) + hi16(tw.z) * __frcp_rn(1.0f + __expf(-a1[1]));
;                     const float o6 = lo16(xw.w) + lo16(tw.w) * __frcp_rn(1.0f + __expf(-a1[2])), o7 = hi16(xw.w) + hi16(tw.w) * __frcp_rn(1.0f + __expf(-a1[3]));
;                     u32x4 w; w.x = pk2(o0, o1); w.y = pk2(o2, o3); w.z = pk2(o4, o5); w.w = pk2(o6, o7); *(u32x4*)(xbo + off) = w;
;                     part += ((o0 * o0 + o1 * o1) + (o2 * o2 + o3 * o3)) + ((o4 * o4 + o5 * o5) + (o6 * o6 + o7 * o7)); }
;                 part += __shfl_xor(part, 16); part += __shfl_xor(part, 32);
;                 if (ssout && fq == 0) ssout[(size_t)row * 16 + u.pn * 4 + wc] = part;
.LBB0_484:
	s_or_b64 exec, exec, s[0:1]
	v_add_u32_e32 v24, 0xb0, v142
	v_ashrrev_i32_e32 v25, 31, v24
	s_waitcnt lgkmcnt(0)
	v_lshlrev_b64 v[16:17], 10, v[24:25]
	v_lshl_add_u64 v[16:17], v[16:17], 0, v[140:141]
	v_lshlrev_b64 v[20:21], 1, v[16:17]
	v_lshl_add_u64 v[26:27], s[18:19], 0, v[20:21]
	global_load_dwordx4 v[16:19], v[26:27], off
	v_lshl_add_u64 v[28:29], s[12:13], 0, v[20:21]
	global_load_dwordx4 v[20:23], v[28:29], off
	v_pk_mul_f32 v[12:13], v[12:13], v[138:139] op_sel_hi:[1,0]
	v_pk_mul_f32 v[30:31], v[8:9], v[138:139] op_sel_hi:[1,0]
	v_pk_mul_f32 v[8:9], v[12:13], v[240:241] op_sel_hi:[1,0]
	v_exp_f32_e32 v8, v8
	v_exp_f32_e32 v9, v9
	v_pk_mul_f32 v[14:15], v[14:15], v[138:139] op_sel_hi:[1,0]
	v_pk_mul_f32 v[10:11], v[10:11], v[138:139] op_sel_hi:[1,0]
	v_pk_mul_f32 v[4:5], v[4:5], v[138:139] op_sel_hi:[1,0]
	v_pk_add_f32 v[8:9], v[8:9], 1.0 op_sel_hi:[1,0]
	v_mul_f32_e32 v10, 0xbfb8aa3b, v10
	v_mul_f32_e32 v11, 0xbfb8aa3b, v11
	v_exp_f32_e32 v10, v10
	v_exp_f32_e32 v11, v11
	v_pk_mul_f32 v[6:7], v[6:7], v[138:139] op_sel_hi:[1,0]
	v_pk_mul_f32 v[2:3], v[2:3], v[138:139] op_sel_hi:[1,0]
	v_pk_add_f32 v[10:11], v[10:11], 1.0 op_sel_hi:[1,0]
	v_mul_f32_e32 v2, 0xbfb8aa3b, v2
	v_mul_f32_e32 v3, 0xbfb8aa3b, v3
	v_exp_f32_e32 v2, v2
	v_exp_f32_e32 v3, v3
	s_waitcnt vmcnt(1)
	v_lshlrev_b32_e32 v32, 16, v16
	v_and_b32_e32 v33, 0xffff0000, v16
	s_waitcnt vmcnt(0)
	v_lshlrev_b32_e32 v12, 16, v20
	v_and_b32_e32 v13, 0xffff0000, v20
	v_pk_add_f32 v[2:3], v[2:3], 1.0 op_sel_hi:[1,0]
	v_rcp_f32_e32 v9, v9
	v_rcp_f32_e32 v8, v8
	s_nop 0
	v_pk_fma_f32 v[8:9], v[8:9], v[32:33], v[12:13]
	v_pk_mul_f32 v[12:13], v[14:15], v[240:241] op_sel_hi:[1,0]
	v_exp_f32_e32 v12, v12
	v_exp_f32_e32 v13, v13
	v_lshlrev_b32_e32 v14, 16, v21
	v_and_b32_e32 v15, 0xffff0000, v21
	v_lshlrev_b32_e32 v16, 16, v17
	v_pk_add_f32 v[12:13], v[12:13], 1.0 op_sel_hi:[1,0]
	v_and_b32_e32 v17, 0xffff0000, v17
	v_rcp_f32_e32 v13, v13
	v_rcp_f32_e32 v12, v12
	s_nop 0
	v_pk_fma_f32 v[14:15], v[12:13], v[16:17], v[14:15]
	v_pk_mul_f32 v[12:13], v[30:31], v[240:241] op_sel_hi:[1,0]
	v_exp_f32_e32 v12, v12
	v_exp_f32_e32 v13, v13
	v_lshlrev_b32_e32 v20, 16, v18
	v_and_b32_e32 v21, 0xffff0000, v18
	v_lshlrev_b32_e32 v16, 16, v22
	v_pk_add_f32 v[12:13], v[12:13], 1.0 op_sel_hi:[1,0]
	v_and_b32_e32 v17, 0xffff0000, v22
	v_rcp_f32_e32 v13, v13
	v_rcp_f32_e32 v12, v12
	s_nop 0
	v_pk_fma_f32 v[20:21], v[12:13], v[20:21], v[16:17]
	v_lshlrev_b32_e32 v16, 16, v19
	v_and_b32_e32 v17, 0xffff0000, v19
	v_lshlrev_b32_e32 v12, 16, v23
	v_and_b32_e32 v13, 0xffff0000, v23
	v_rcp_f32_e32 v11, v11
	v_rcp_f32_e32 v10, v10
	s_nop 0
	v_pk_fma_f32 v[22:23], v[10:11], v[16:17], v[12:13]
	v_cvt_pk_bf16_f32 v10, v8, v9
	v_cvt_pk_bf16_f32 v11, v14, v15
	v_cvt_pk_bf16_f32 v12, v20, v21
	v_cvt_pk_bf16_f32 v13, v22, v23
	global_store_dwordx4 v[26:27], v[10:13], off
	v_pk_mul_f32 v[16:17], v[8:9], v[8:9]
	v_pk_mul_f32 v[18:19], v[14:15], v[14:15]
	global_load_dwordx4 v[8:11], v[26:27], off offset:256
	global_load_dwordx4 v[12:15], v[28:29], off offset:256
	v_pk_mul_f32 v[28:29], v[0:1], v[138:139] op_sel_hi:[1,0]
	v_pk_mul_f32 v[0:1], v[4:5], v[240:241] op_sel_hi:[1,0]
	v_exp_f32_e32 v0, v0
	v_exp_f32_e32 v1, v1
	v_pk_mul_f32 v[20:21], v[20:21], v[20:21]
	v_pk_mul_f32 v[22:23], v[22:23], v[22:23]
	v_pk_add_f32 v[0:1], v[0:1], 1.0 op_sel_hi:[1,0]
	s_waitcnt vmcnt(1)
	v_lshlrev_b32_e32 v30, 16, v8
	v_and_b32_e32 v31, 0xffff0000, v8
	s_waitcnt vmcnt(0)
	v_lshlrev_b32_e32 v4, 16, v12
	v_and_b32_e32 v5, 0xffff0000, v12
	v_rcp_f32_e32 v1, v1
	v_rcp_f32_e32 v0, v0
	s_nop 0
	v_pk_fma_f32 v[0:1], v[0:1], v[30:31], v[4:5]
	v_pk_mul_f32 v[4:5], v[6:7], v[240:241] op_sel_hi:[1,0]
	v_exp_f32_e32 v4, v4
	v_exp_f32_e32 v5, v5
	v_lshlrev_b32_e32 v6, 16, v13
	v_and_b32_e32 v7, 0xffff0000, v13
	v_lshlrev_b32_e32 v8, 16, v9
	v_pk_add_f32 v[4:5], v[4:5], 1.0 op_sel_hi:[1,0]
	v_and_b32_e32 v9, 0xffff0000, v9
	v_rcp_f32_e32 v5, v5
	v_rcp_f32_e32 v4, v4
	s_nop 0
	v_pk_fma_f32 v[4:5], v[4:5], v[8:9], v[6:7]
	v_pk_mul_f32 v[6:7], v[28:29], v[240:241] op_sel_hi:[1,0]
	v_exp_f32_e32 v6, v6
	v_exp_f32_e32 v7, v7
	v_lshlrev_b32_e32 v12, 16, v10
	v_and_b32_e32 v13, 0xffff0000, v10
	v_lshlrev_b32_e32 v8, 16, v14
	v_pk_add_f32 v[6:7], v[6:7], 1.0 op_sel_hi:[1,0]
	v_and_b32_e32 v9, 0xffff0000, v14
	v_rcp_f32_e32 v7, v7
	v_rcp_f32_e32 v6, v6
	s_nop 0
	v_pk_fma_f32 v[12:13], v[6:7], v[12:13], v[8:9]
	v_lshlrev_b32_e32 v8, 16, v11
	v_and_b32_e32 v9, 0xffff0000, v11
	v_lshlrev_b32_e32 v6, 16, v15
	v_and_b32_e32 v7, 0xffff0000, v15
	v_rcp_f32_e32 v3, v3
	v_rcp_f32_e32 v2, v2
	s_nop 0
	v_pk_fma_f32 v[2:3], v[2:3], v[8:9], v[6:7]
	v_cvt_pk_bf16_f32 v6, v0, v1
	v_cvt_pk_bf16_f32 v7, v4, v5
	v_cvt_pk_bf16_f32 v8, v12, v13
	v_cvt_pk_bf16_f32 v9, v2, v3
	global_store_dwordx4 v[26:27], v[6:9], off offset:256
	v_pk_mul_f32 v[2:3], v[2:3], v[2:3]
	v_pk_mul_f32 v[0:1], v[0:1], v[0:1]
	v_pk_mul_f32 v[6:7], v[12:13], v[12:13]
	v_pk_mul_f32 v[4:5], v[4:5], v[4:5]
	v_add_f32_e32 v8, v22, v23
	v_add_f32_e32 v9, v20, v21
	v_add_f32_e32 v2, v2, v3
	v_add_f32_e32 v3, v6, v7
	v_add_f32_e32 v8, v9, v8
	v_add_f32_e32 v9, v18, v19
	v_add_f32_e32 v10, v16, v17
	v_add_f32_e32 v2, v3, v2
	v_add_f32_e32 v3, v4, v5
	v_add_f32_e32 v0, v0, v1
	v_add_f32_e32 v9, v10, v9
	v_add_f32_e32 v0, v0, v3
	v_add_f32_e32 v8, v9, v8
	v_add_f32_e32 v0, v0, v2
	v_add_f32_e32 v0, v8, v0
	ds_bpermute_b32 v1, v169, v0
	s_waitcnt lgkmcnt(0)
	v_add_f32_e32 v0, v0, v1
	ds_bpermute_b32 v1, v155, v0
	s_and_saveexec_b64 s[0:1], s[46:47]
	s_cbranch_execz .LBB0_486
	s_waitcnt lgkmcnt(0)
	v_add_f32_e32 v2, v0, v1
	v_lshlrev_b64 v[0:1], 6, v[24:25]
	v_lshl_add_u64 v[0:1], s[6:7], 0, v[0:1]
	v_lshl_add_u64 v[0:1], s[42:43], 2, v[0:1]
	s_lshl_b32 s94, s35, 2
	v_lshl_add_u64 v[0:1], v[0:1], 0, s[94:95]
	global_store_dword v[0:1], v2, off

; DI float rowscale(const float* ss, int row) {
;     const f32x4* p = (const f32x4*)(ss + (size_t)row * 16);
;     const f32x4 a = p[0], b = p[1], c = p[2], d = p[3];
;     const float s = (((a.x + a.y) + (a.z + a.w)) + ((b.x + b.y) + (b.z + b.w))) + (((c.x + c.y) + (c.z + c.w)) + ((d.x + d.y) + (d.z + d.w)));
;     return rsqrtf(s * (1.0f / 1024.0f) + EPS);
; }
; DI void rowscales8(const float* ss, int rowbase, int fr, int fq, float (&r)[2][4]) {
;     const int lane = fq * 16 + fr;
;     const float rA = rowscale(ss, rowbase + lane), rB = rowscale(ss, rowbase + 128 + lane);
; #pragma unroll
;     for (int m = 0; m < 4; ++m) { r[0][m] = __shfl(rA, m * 16 + fr); r[1][m] = __shfl(rB, m * 16 + fr); }
; }
;     DI void operator()(const pg8::f32x4 (&acc)[2][2][4][2], const pg8::Unit& u, int wr, int wc, int fr, int fq) const {
;         const int row0 = u.pm * 256 + wr * 64 + fr, col0 = u.pn * 128 + wc * 32 + 8 * fq;
;         float rs[2][4]; rowscales8(ss, u.pm * 256 + wr * 64, fr, fq, rs);
; #pragma unroll
;         for (int ai = 0; ai < 2; ++ai)
; #pragma unroll
;             for (int m = 0; m < 4; ++m) {
;                 const int row = row0 + ai * 128 + m * 16; const float r = rs[ai][m];
;                 float hv[8];
; #pragma unroll
;                 for (int n = 0; n < 2; ++n) { const pg8::f32x4 g = acc[ai][0][m][n] * r, uu = acc[ai][1][m][n] * r;
; #pragma unroll
;                     for (int e = 0; e < 4; ++e) hv[4 * n + e] = g[e] * __frcp_rn(1.0f + __expf(-g[e])) * uu[e]; }
.LBB0_520:
	v_mov_b32_e32 v240, 0xbfb8aa3b
	s_lshl_b32 s9, s16, 8
	s_add_i32 s9, s9, s48
	v_or_b32_e32 v154, s9, v143
	v_ashrrev_i32_e32 v155, 31, v154
	v_lshlrev_b64 v[154:155], 6, v[154:155]
	v_lshl_add_u64 v[158:159], s[4:5], 0, v[154:155]
	global_load_dwordx4 v[154:157], v[158:159], off offset:16
	global_load_dwordx4 v[162:165], v[158:159], off offset:48
	global_load_dwordx4 v[166:169], v[158:159], off
	global_load_dwordx4 v[170:173], v[158:159], off offset:32
	v_add_u32_e32 v232, s9, v145
	v_ashrrev_i32_e32 v233, 31, v232
	v_lshlrev_b64 v[232:233], 6, v[232:233]
	v_lshl_add_u64 v[230:231], s[4:5], 0, v[232:233]
	global_load_dwordx4 v[214:217], v[230:231], off offset:16
	global_load_dwordx4 v[218:221], v[230:231], off offset:48
	global_load_dwordx4 v[222:225], v[230:231], off
	global_load_dwordx4 v[226:229], v[230:231], off offset:32
	s_mov_b32 s16, 0x3a800000
	v_lshl_or_b32 v152, s17, 7, v147
	v_or_b32_e32 v151, s9, v139
	s_mul_i32 s11, s88, 56
	s_waitcnt vmcnt(4)
	v_mov_b32_e32 v158, v166
	v_mov_b32_e32 v159, v170
	v_mov_b32_e32 v170, v167
	v_mov_b32_e32 v166, v168
	v_mov_b32_e32 v167, v172
	v_mov_b32_e32 v172, v169
	v_pk_add_f32 v[158:159], v[158:159], v[170:171]
	v_pk_add_f32 v[166:167], v[166:167], v[172:173]
	v_pk_add_f32 v[158:159], v[158:159], v[166:167]
	v_mov_b32_e32 v166, v154
	v_mov_b32_e32 v167, v162
	v_mov_b32_e32 v162, v155
	v_pk_add_f32 v[154:155], v[166:167], v[162:163]
	v_mov_b32_e32 v162, v156
	v_mov_b32_e32 v163, v164
	v_mov_b32_e32 v164, v157
	v_pk_add_f32 v[156:157], v[162:163], v[164:165]
	v_pk_add_f32 v[154:155], v[154:155], v[156:157]
	v_pk_add_f32 v[158:159], v[158:159], v[154:155]
	s_waitcnt vmcnt(0)
	v_mov_b64_e32 v[154:155], v[214:215]
	v_mov_b64_e32 v[156:157], v[216:217]
	v_mov_b64_e32 v[162:163], v[218:219]
	v_mov_b64_e32 v[164:165], v[220:221]
	v_mov_b64_e32 v[166:167], v[222:223]
	v_mov_b64_e32 v[168:169], v[224:225]
	v_mov_b64_e32 v[170:171], v[226:227]
	v_mov_b64_e32 v[172:173], v[228:229]
	s_movk_i32 s9, 0x1600
	v_mov_b32_e32 v174, v166
	v_mov_b32_e32 v175, v170
	v_mov_b32_e32 v170, v167
	v_pk_add_f32 v[166:167], v[174:175], v[170:171]
	v_mov_b32_e32 v170, v168
	v_mov_b32_e32 v171, v172
	v_mov_b32_e32 v172, v169
	v_pk_add_f32 v[168:169], v[170:171], v[172:173]
	v_pk_add_f32 v[166:167], v[166:167], v[168:169]
	v_mov_b32_e32 v168, v154
	v_mov_b32_e32 v169, v162
	v_mov_b32_e32 v162, v155
	v_pk_add_f32 v[154:155], v[168:169], v[162:163]
	v_mov_b32_e32 v162, v156
	v_mov_b32_e32 v163, v164
	v_mov_b32_e32 v164, v157
	v_pk_add_f32 v[156:157], v[162:163], v[164:165]
	v_pk_add_f32 v[154:155], v[154:155], v[156:157]
	v_mov_b32_e32 v157, v158
	v_pk_add_f32 v[154:155], v[166:167], v[154:155]
	v_mov_b32_e32 v156, v154
	v_mov_b32_e32 v158, v155
	v_pk_add_f32 v[154:155], v[156:157], v[158:159]
	v_pk_fma_f32 v[154:155], v[154:155], s[16:17], v[176:177] op_sel_hi:[1,0,0]
	v_mul_f32_e32 v138, 0x4b800000, v155
	v_cmp_gt_f32_e64 s[42:43], s39, v155
	v_cmp_gt_f32_e32 vcc, s39, v154
	s_nop 0
	v_cndmask_b32_e64 v138, v155, v138, s[42:43]
	v_rsq_f32_e32 v138, v138
	s_nop 0
	v_mul_f32_e32 v140, 0x45800000, v138
	v_cndmask_b32_e64 v138, v138, v140, s[42:43]
	v_mul_f32_e32 v140, 0x4b800000, v154
	v_cndmask_b32_e32 v140, v154, v140, vcc
	v_rsq_f32_e32 v140, v140
	s_nop 0
	v_mul_f32_e32 v142, 0x45800000, v140
	v_cndmask_b32_e32 v153, v140, v142, vcc
	v_and_or_b32 v140, v177, 64, v139
	v_lshlrev_b32_e32 v155, 2, v140
	ds_bpermute_b32 v154, v155, v138
	ds_bpermute_b32 v144, v155, v153
	ds_bpermute_b32 v150, v155, v138 offset:64
	ds_bpermute_b32 v142, v155, v153 offset:64
	ds_bpermute_b32 v148, v155, v138 offset:128
	s_waitcnt lgkmcnt(4)
	v_pk_mul_f32 v[124:125], v[124:125], v[154:155] op_sel_hi:[1,0]
	ds_bpermute_b32 v140, v155, v153 offset:128
	ds_bpermute_b32 v146, v155, v138 offset:192
	ds_bpermute_b32 v138, v155, v153 offset:192
	v_mul_f32_e32 v155, 0xbfb8aa3b, v124
	v_exp_f32_e32 v156, v155
	v_mul_f32_e32 v155, 0xbfb8aa3b, v125
	v_exp_f32_e32 v157, v155
	v_ashrrev_i32_e32 v153, 31, v152
	s_waitcnt lgkmcnt(5)
	v_pk_mul_f32 v[108:109], v[108:109], v[150:151] op_sel_hi:[1,0]
	v_pk_mul_f32 v[104:105], v[104:105], v[150:151] op_sel_hi:[1,0]
	v_pk_add_f32 v[156:157], v[156:157], 1.0 op_sel_hi:[1,0]
	v_pk_mul_f32 v[106:107], v[106:107], v[150:151] op_sel_hi:[1,0]
	v_pk_mul_f32 v[100:101], v[100:101], v[150:151] op_sel_hi:[1,0]
	v_pk_mul_f32 v[96:97], v[96:97], v[150:151] op_sel_hi:[1,0]
	v_pk_mul_f32 v[98:99], v[98:99], v[150:151] op_sel_hi:[1,0]
	v_rcp_f32_e32 v157, v157
	s_waitcnt lgkmcnt(3)
	v_pk_mul_f32 v[92:93], v[92:93], v[148:149] op_sel_hi:[1,0]
	v_pk_mul_f32 v[88:89], v[88:89], v[148:149] op_sel_hi:[1,0]
	v_pk_mul_f32 v[90:91], v[90:91], v[148:149] op_sel_hi:[1,0]
	v_rcp_f32_e32 v156, v156
	s_nop 0
	v_pk_mul_f32 v[124:125], v[124:125], v[156:157]
	v_pk_mul_f32 v[120:121], v[120:121], v[154:155] op_sel_hi:[1,0]
	v_pk_mul_f32 v[84:85], v[84:85], v[148:149] op_sel_hi:[1,0]
	v_pk_mul_f32 v[120:121], v[120:121], v[124:125]
	v_pk_mul_f32 v[124:125], v[126:127], v[154:155] op_sel_hi:[1,0]
	v_pk_mul_f32 v[80:81], v[80:81], v[148:149] op_sel_hi:[1,0]
	v_pk_mul_f32 v[126:127], v[124:125], v[240:241] op_sel_hi:[1,0]
	v_exp_f32_e32 v126, v126
	v_exp_f32_e32 v127, v127
	v_pk_mul_f32 v[82:83], v[82:83], v[148:149] op_sel_hi:[1,0]
	s_waitcnt lgkmcnt(1)
; DI unsigned pk2(float lo, float hi) { const f32x2_t v = {lo, hi}; const bf16x2_t b = __builtin_convertvector(v, bf16x2_t); return __builtin_bit_cast(unsigned, b); }
;     DI void operator()(const pg8::f32x4 (&acc)[2][2][4][2], const pg8::Unit& u, int wr, int wc, int fr, int fq) const {
;     ...
; #pragma unroll
;         for (int ai = 0; ai < 2; ++ai)
; #pragma unroll
;             for (int m = 0; m < 4; ++m) {
;                 const int row = row0 + ai * 128 + m * 16; const float r = rs[ai][m];
;                 float hv[8];
; #pragma unroll
;                 for (int n = 0; n < 2; ++n) { const pg8::f32x4 g = acc[ai][0][m][n] * r, uu = acc[ai][1][m][n] * r;
; #pragma unroll
;                     for (int e = 0; e < 4; ++e) hv[4 * n + e] = g[e] * __frcp_rn(1.0f + __expf(-g[e])) * uu[e]; }
;                 u32x4 w; w.x = pk2(hv[0], hv[1]); w.y = pk2(hv[2], hv[3]); w.z = pk2(hv[4], hv[5]); w.w = pk2(hv[6], hv[7]);
;                 *(u32x4*)(H + (size_t)row * DFF + col0) = w;
;             }
	v_pk_mul_f32 v[76:77], v[76:77], v[146:147] op_sel_hi:[1,0]
	v_pk_mul_f32 v[72:73], v[72:73], v[146:147] op_sel_hi:[1,0]
	v_pk_add_f32 v[126:127], v[126:127], 1.0 op_sel_hi:[1,0]
	v_pk_mul_f32 v[74:75], v[74:75], v[146:147] op_sel_hi:[1,0]
	v_pk_mul_f32 v[68:69], v[68:69], v[146:147] op_sel_hi:[1,0]
	v_pk_mul_f32 v[64:65], v[64:65], v[146:147] op_sel_hi:[1,0]
	v_pk_mul_f32 v[66:67], v[66:67], v[146:147] op_sel_hi:[1,0]
	v_rcp_f32_e32 v127, v127
	v_pk_mul_f32 v[60:61], v[60:61], v[144:145] op_sel_hi:[1,0]
	v_pk_mul_f32 v[56:57], v[56:57], v[144:145] op_sel_hi:[1,0]
	v_pk_mul_f32 v[58:59], v[58:59], v[144:145] op_sel_hi:[1,0]
	v_rcp_f32_e32 v126, v126
	s_nop 0
	v_pk_mul_f32 v[124:125], v[124:125], v[126:127]
	v_pk_mul_f32 v[122:123], v[122:123], v[154:155] op_sel_hi:[1,0]
	v_pk_mul_f32 v[116:117], v[116:117], v[154:155] op_sel_hi:[1,0]
	v_pk_mul_f32 v[122:123], v[122:123], v[124:125]
	v_pk_mul_f32 v[124:125], v[116:117], v[240:241] op_sel_hi:[1,0]
	v_exp_f32_e32 v124, v124
	v_exp_f32_e32 v125, v125
	v_pk_mul_f32 v[52:53], v[52:53], v[144:145] op_sel_hi:[1,0]
	v_pk_mul_f32 v[48:49], v[48:49], v[144:145] op_sel_hi:[1,0]
	v_pk_mul_f32 v[50:51], v[50:51], v[144:145] op_sel_hi:[1,0]
	v_pk_add_f32 v[124:125], v[124:125], 1.0 op_sel_hi:[1,0]
	v_pk_mul_f32 v[44:45], v[44:45], v[142:143] op_sel_hi:[1,0]
	v_pk_mul_f32 v[40:41], v[40:41], v[142:143] op_sel_hi:[1,0]
	v_pk_mul_f32 v[42:43], v[42:43], v[142:143] op_sel_hi:[1,0]
	v_pk_mul_f32 v[36:37], v[36:37], v[142:143] op_sel_hi:[1,0]
	v_rcp_f32_e32 v125, v125
	v_pk_mul_f32 v[32:33], v[32:33], v[142:143] op_sel_hi:[1,0]
	v_pk_mul_f32 v[34:35], v[34:35], v[142:143] op_sel_hi:[1,0]
	v_pk_mul_f32 v[28:29], v[28:29], v[140:141] op_sel_hi:[1,0]
	v_rcp_f32_e32 v124, v124
	s_nop 0
	v_pk_mul_f32 v[116:117], v[116:117], v[124:125]
	v_pk_mul_f32 v[112:113], v[112:113], v[154:155] op_sel_hi:[1,0]
	v_pk_mul_f32 v[24:25], v[24:25], v[140:141] op_sel_hi:[1,0]
	v_pk_mul_f32 v[112:113], v[112:113], v[116:117]
	v_pk_mul_f32 v[116:117], v[118:119], v[154:155] op_sel_hi:[1,0]
	v_pk_mul_f32 v[26:27], v[26:27], v[140:141] op_sel_hi:[1,0]
	v_pk_mul_f32 v[118:119], v[116:117], v[240:241] op_sel_hi:[1,0]
	v_exp_f32_e32 v118, v118
	v_exp_f32_e32 v119, v119
	v_pk_mul_f32 v[20:21], v[20:21], v[140:141] op_sel_hi:[1,0]
	v_pk_mul_f32 v[16:17], v[16:17], v[140:141] op_sel_hi:[1,0]
	v_pk_mul_f32 v[18:19], v[18:19], v[140:141] op_sel_hi:[1,0]
	v_pk_add_f32 v[118:119], v[118:119], 1.0 op_sel_hi:[1,0]
	s_waitcnt lgkmcnt(0)
	v_pk_mul_f32 v[12:13], v[12:13], v[138:139] op_sel_hi:[1,0]
	v_pk_mul_f32 v[8:9], v[8:9], v[138:139] op_sel_hi:[1,0]
	v_pk_mul_f32 v[10:11], v[10:11], v[138:139] op_sel_hi:[1,0]
	v_pk_mul_f32 v[4:5], v[4:5], v[138:139] op_sel_hi:[1,0]
	v_rcp_f32_e32 v119, v119
	v_pk_mul_f32 v[0:1], v[0:1], v[138:139] op_sel_hi:[1,0]
	v_pk_mul_f32 v[2:3], v[2:3], v[138:139] op_sel_hi:[1,0]
	v_rcp_f32_e32 v118, v118
	s_nop 0
	v_pk_mul_f32 v[116:117], v[116:117], v[118:119]
	v_pk_mul_f32 v[114:115], v[114:115], v[154:155] op_sel_hi:[1,0]
	v_cvt_pk_bf16_f32 v118, v112, v113
	v_pk_mul_f32 v[114:115], v[114:115], v[116:117]
	v_mov_b64_e32 v[112:113], s[82:83]
	v_cvt_pk_bf16_f32 v116, v120, v121
	v_cvt_pk_bf16_f32 v119, v114, v115
	v_mad_i64_i32 v[120:121], s[16:17], v151, s9, v[112:113]
	v_lshlrev_b64 v[114:115], 1, v[152:153]
	v_cvt_pk_bf16_f32 v117, v122, v123
	v_lshl_add_u64 v[120:121], v[120:121], 0, v[114:115]
	global_store_dwordx4 v[120:121], v[116:119], off
	s_nop 1
	v_pk_mul_f32 v[116:117], v[108:109], v[240:241] op_sel_hi:[1,0]
	v_exp_f32_e32 v116, v116
	v_exp_f32_e32 v117, v117
	s_nop 0
	v_pk_add_f32 v[116:117], v[116:117], 1.0 op_sel_hi:[1,0]
	v_rcp_f32_e32 v117, v117
	v_rcp_f32_e32 v116, v116
	s_nop 0
	v_pk_mul_f32 v[108:109], v[108:109], v[116:117]
	v_pk_mul_f32 v[104:105], v[104:105], v[108:109]
	v_pk_mul_f32 v[108:109], v[110:111], v[150:151] op_sel_hi:[1,0]
	v_pk_mul_f32 v[110:111], v[108:109], v[240:241] op_sel_hi:[1,0]
	v_exp_f32_e32 v110, v110
	v_exp_f32_e32 v111, v111
	s_nop 0
	v_pk_add_f32 v[110:111], v[110:111], 1.0 op_sel_hi:[1,0]
	v_rcp_f32_e32 v111, v111
	v_rcp_f32_e32 v110, v110
	s_nop 0
	v_pk_mul_f32 v[108:109], v[108:109], v[110:111]
	v_pk_mul_f32 v[106:107], v[106:107], v[108:109]
	v_pk_mul_f32 v[108:109], v[100:101], v[240:241] op_sel_hi:[1,0]
	v_exp_f32_e32 v108, v108
	v_exp_f32_e32 v109, v109
	s_nop 0
	v_pk_add_f32 v[108:109], v[108:109], 1.0 op_sel_hi:[1,0]
	v_rcp_f32_e32 v109, v109
	v_rcp_f32_e32 v108, v108
	s_nop 0
	v_pk_mul_f32 v[100:101], v[100:101], v[108:109]
	v_pk_mul_f32 v[100:101], v[96:97], v[100:101]
	v_pk_mul_f32 v[96:97], v[102:103], v[150:151] op_sel_hi:[1,0]
	v_pk_mul_f32 v[102:103], v[96:97], v[240:241] op_sel_hi:[1,0]
	v_exp_f32_e32 v102, v102
	v_exp_f32_e32 v103, v103
	s_nop 0
	v_pk_add_f32 v[102:103], v[102:103], 1.0 op_sel_hi:[1,0]
	v_rcp_f32_e32 v103, v103
	v_rcp_f32_e32 v102, v102
	s_nop 0
	v_pk_mul_f32 v[96:97], v[96:97], v[102:103]
	v_or_b32_e32 v108, 16, v151
	v_pk_mul_f32 v[102:103], v[98:99], v[96:97]
	v_cvt_pk_bf16_f32 v98, v100, v101
	v_mad_i64_i32 v[100:101], s[16:17], v108, s9, v[112:113]
	v_cvt_pk_bf16_f32 v96, v104, v105
	v_cvt_pk_bf16_f32 v97, v106, v107
	v_cvt_pk_bf16_f32 v99, v102, v103
	v_lshl_add_u64 v[100:101], v[100:101], 0, v[114:115]
	global_store_dwordx4 v[100:101], v[96:99], off
	s_nop 1
	v_pk_mul_f32 v[96:97], v[92:93], v[240:241] op_sel_hi:[1,0]
	v_exp_f32_e32 v96, v96
	v_exp_f32_e32 v97, v97
	s_nop 0
	v_pk_add_f32 v[96:97], v[96:97], 1.0 op_sel_hi:[1,0]
	v_rcp_f32_e32 v97, v97
	v_rcp_f32_e32 v96, v96
	s_nop 0
	v_pk_mul_f32 v[92:93], v[92:93], v[96:97]
	v_pk_mul_f32 v[88:89], v[88:89], v[92:93]
	v_pk_mul_f32 v[92:93], v[94:95], v[148:149] op_sel_hi:[1,0]
; DI unsigned pk2(float lo, float hi) { const f32x2_t v = {lo, hi}; const bf16x2_t b = __builtin_convertvector(v, bf16x2_t); return __builtin_bit_cast(unsigned, b); }
;     DI void operator()(const pg8::f32x4 (&acc)[2][2][4][2], const pg8::Unit& u, int wr, int wc, int fr, int fq) const {
;     ...
; #pragma unroll
;         for (int ai = 0; ai < 2; ++ai)
; #pragma unroll
;             for (int m = 0; m < 4; ++m) {
;                 const int row = row0 + ai * 128 + m * 16; const float r = rs[ai][m];
;                 float hv[8];
; #pragma unroll
;                 for (int n = 0; n < 2; ++n) { const pg8::f32x4 g = acc[ai][0][m][n] * r, uu = acc[ai][1][m][n] * r;
; #pragma unroll
;                     for (int e = 0; e < 4; ++e) hv[4 * n + e] = g[e] * __frcp_rn(1.0f + __expf(-g[e])) * uu[e]; }
;                 u32x4 w; w.x = pk2(hv[0], hv[1]); w.y = pk2(hv[2], hv[3]); w.z = pk2(hv[4], hv[5]); w.w = pk2(hv[6], hv[7]);
;                 *(u32x4*)(H + (size_t)row * DFF + col0) = w;
;             }
	v_pk_mul_f32 v[94:95], v[92:93], v[240:241] op_sel_hi:[1,0]
	v_exp_f32_e32 v94, v94
	v_exp_f32_e32 v95, v95
	s_nop 0
	v_pk_add_f32 v[94:95], v[94:95], 1.0 op_sel_hi:[1,0]
	v_rcp_f32_e32 v95, v95
	v_rcp_f32_e32 v94, v94
	s_nop 0
	v_pk_mul_f32 v[92:93], v[92:93], v[94:95]
	v_pk_mul_f32 v[90:91], v[90:91], v[92:93]
	v_pk_mul_f32 v[92:93], v[84:85], v[240:241] op_sel_hi:[1,0]
	v_exp_f32_e32 v92, v92
	v_exp_f32_e32 v93, v93
	s_nop 0
	v_pk_add_f32 v[92:93], v[92:93], 1.0 op_sel_hi:[1,0]
	v_rcp_f32_e32 v93, v93
	v_rcp_f32_e32 v92, v92
	s_nop 0
	v_pk_mul_f32 v[84:85], v[84:85], v[92:93]
	v_pk_mul_f32 v[84:85], v[80:81], v[84:85]
	v_pk_mul_f32 v[80:81], v[86:87], v[148:149] op_sel_hi:[1,0]
	v_pk_mul_f32 v[86:87], v[80:81], v[240:241] op_sel_hi:[1,0]
	v_exp_f32_e32 v86, v86
	v_exp_f32_e32 v87, v87
	s_nop 0
	v_pk_add_f32 v[86:87], v[86:87], 1.0 op_sel_hi:[1,0]
	v_rcp_f32_e32 v87, v87
	v_rcp_f32_e32 v86, v86
	s_nop 0
	v_pk_mul_f32 v[80:81], v[80:81], v[86:87]
	v_or_b32_e32 v92, 32, v151
	v_pk_mul_f32 v[86:87], v[82:83], v[80:81]
	v_cvt_pk_bf16_f32 v82, v84, v85
	v_mad_i64_i32 v[84:85], s[16:17], v92, s9, v[112:113]
	v_cvt_pk_bf16_f32 v80, v88, v89
	v_cvt_pk_bf16_f32 v81, v90, v91
	v_cvt_pk_bf16_f32 v83, v86, v87
	v_lshl_add_u64 v[84:85], v[84:85], 0, v[114:115]
	global_store_dwordx4 v[84:85], v[80:83], off
	s_nop 1
	v_pk_mul_f32 v[80:81], v[76:77], v[240:241] op_sel_hi:[1,0]
	v_exp_f32_e32 v80, v80
	v_exp_f32_e32 v81, v81
	s_nop 0
	v_pk_add_f32 v[80:81], v[80:81], 1.0 op_sel_hi:[1,0]
	v_rcp_f32_e32 v81, v81
	v_rcp_f32_e32 v80, v80
	s_nop 0
	v_pk_mul_f32 v[76:77], v[76:77], v[80:81]
	v_pk_mul_f32 v[72:73], v[72:73], v[76:77]
	v_pk_mul_f32 v[76:77], v[78:79], v[146:147] op_sel_hi:[1,0]
	v_pk_mul_f32 v[78:79], v[76:77], v[240:241] op_sel_hi:[1,0]
	v_exp_f32_e32 v78, v78
	v_exp_f32_e32 v79, v79
	s_nop 0
	v_pk_add_f32 v[78:79], v[78:79], 1.0 op_sel_hi:[1,0]
	v_rcp_f32_e32 v79, v79
	v_rcp_f32_e32 v78, v78
	s_nop 0
	v_pk_mul_f32 v[76:77], v[76:77], v[78:79]
	v_pk_mul_f32 v[74:75], v[74:75], v[76:77]
	v_pk_mul_f32 v[76:77], v[68:69], v[240:241] op_sel_hi:[1,0]
	v_exp_f32_e32 v76, v76
	v_exp_f32_e32 v77, v77
	s_nop 0
	v_pk_add_f32 v[76:77], v[76:77], 1.0 op_sel_hi:[1,0]
	v_rcp_f32_e32 v77, v77
	v_rcp_f32_e32 v76, v76
	s_nop 0
	v_pk_mul_f32 v[68:69], v[68:69], v[76:77]
	v_pk_mul_f32 v[68:69], v[64:65], v[68:69]
	v_pk_mul_f32 v[64:65], v[70:71], v[146:147] op_sel_hi:[1,0]
	v_pk_mul_f32 v[70:71], v[64:65], v[240:241] op_sel_hi:[1,0]
	v_exp_f32_e32 v70, v70
	v_exp_f32_e32 v71, v71
	s_nop 0
	v_pk_add_f32 v[70:71], v[70:71], 1.0 op_sel_hi:[1,0]
	v_rcp_f32_e32 v71, v71
	v_rcp_f32_e32 v70, v70
	s_nop 0
	v_pk_mul_f32 v[64:65], v[64:65], v[70:71]
	v_or_b32_e32 v76, 48, v151
	v_pk_mul_f32 v[70:71], v[66:67], v[64:65]
	v_cvt_pk_bf16_f32 v66, v68, v69
	v_mad_i64_i32 v[68:69], s[16:17], v76, s9, v[112:113]
	v_cvt_pk_bf16_f32 v64, v72, v73
	v_cvt_pk_bf16_f32 v65, v74, v75
	v_cvt_pk_bf16_f32 v67, v70, v71
	v_lshl_add_u64 v[68:69], v[68:69], 0, v[114:115]
	global_store_dwordx4 v[68:69], v[64:67], off
	s_nop 1
	v_pk_mul_f32 v[64:65], v[60:61], v[240:241] op_sel_hi:[1,0]
	v_exp_f32_e32 v64, v64
	v_exp_f32_e32 v65, v65
	v_add_u32_e32 v66, 0x80, v151
	v_pk_add_f32 v[64:65], v[64:65], 1.0 op_sel_hi:[1,0]
	v_rcp_f32_e32 v65, v65
	v_rcp_f32_e32 v64, v64
	s_nop 0
	v_pk_mul_f32 v[60:61], v[60:61], v[64:65]
	v_pk_mul_f32 v[56:57], v[56:57], v[60:61]
	v_pk_mul_f32 v[60:61], v[62:63], v[144:145] op_sel_hi:[1,0]
	v_pk_mul_f32 v[62:63], v[60:61], v[240:241] op_sel_hi:[1,0]
	v_exp_f32_e32 v62, v62
	v_exp_f32_e32 v63, v63
	s_nop 0
	v_pk_add_f32 v[62:63], v[62:63], 1.0 op_sel_hi:[1,0]
	v_rcp_f32_e32 v63, v63
	v_rcp_f32_e32 v62, v62
	s_nop 0
	v_pk_mul_f32 v[60:61], v[60:61], v[62:63]
	v_pk_mul_f32 v[58:59], v[58:59], v[60:61]
	v_pk_mul_f32 v[60:61], v[52:53], v[240:241] op_sel_hi:[1,0]
	v_exp_f32_e32 v60, v60
	v_exp_f32_e32 v61, v61
	s_nop 0
	v_pk_add_f32 v[60:61], v[60:61], 1.0 op_sel_hi:[1,0]
	v_rcp_f32_e32 v61, v61
	v_rcp_f32_e32 v60, v60
	s_nop 0
	v_pk_mul_f32 v[52:53], v[52:53], v[60:61]
	v_pk_mul_f32 v[52:53], v[48:49], v[52:53]
	v_pk_mul_f32 v[48:49], v[54:55], v[144:145] op_sel_hi:[1,0]
	v_pk_mul_f32 v[54:55], v[48:49], v[240:241] op_sel_hi:[1,0]
	v_exp_f32_e32 v54, v54
	v_exp_f32_e32 v55, v55
	s_nop 0
	v_pk_add_f32 v[54:55], v[54:55], 1.0 op_sel_hi:[1,0]
	v_rcp_f32_e32 v55, v55
	v_rcp_f32_e32 v54, v54
	s_nop 0
	v_pk_mul_f32 v[48:49], v[48:49], v[54:55]
	v_pk_mul_f32 v[54:55], v[50:51], v[48:49]
	v_cvt_pk_bf16_f32 v50, v52, v53
	v_mad_i64_i32 v[52:53], s[16:17], v66, s9, v[112:113]
	v_cvt_pk_bf16_f32 v48, v56, v57
	v_cvt_pk_bf16_f32 v49, v58, v59
	v_cvt_pk_bf16_f32 v51, v54, v55
	v_lshl_add_u64 v[52:53], v[52:53], 0, v[114:115]
	global_store_dwordx4 v[52:53], v[48:51], off
	s_nop 1
	v_pk_mul_f32 v[48:49], v[44:45], v[240:241] op_sel_hi:[1,0]
	v_exp_f32_e32 v48, v48
	v_exp_f32_e32 v49, v49
	s_nop 0
	v_pk_add_f32 v[48:49], v[48:49], 1.0 op_sel_hi:[1,0]
	v_rcp_f32_e32 v49, v49
	v_rcp_f32_e32 v48, v48
	s_nop 0
; #define PG8_BAR __builtin_amdgcn_s_barrier()
; DI unsigned pk2(float lo, float hi) { const f32x2_t v = {lo, hi}; const bf16x2_t b = __builtin_convertvector(v, bf16x2_t); return __builtin_bit_cast(unsigned, b); }
; template <class Epi, class Sched, bool ALIGN_EPI = false, bool SP2 = false>
; __device__ __forceinline__ void gemm_phase(PG8_LAS unsigned char* lds, const Gemm g, const Sched& S, const Epi& E, const int tid) {
;     ...
;         if constexpr (ALIGN_EPI) { if (wr == 0) PG8_BAR; }
;         if constexpr (!Epi::AFTER_DRAIN) { E(acc, cur, wr, wc, fr, fq); S.done(cur); }
;         if (!has_next) break;
; #pragma unroll
;         for (int a = 0; a < 2; ++a)
; #pragma unroll
;             for (int b = 0; b < 2; ++b)
; #pragma unroll
;                 for (int m = 0; m < 4; ++m)
; #pragma unroll
;                     for (int n = 0; n < 2; ++n) acc[a][b][m][n] = (f32x4){0.f, 0.f, 0.f, 0.f};
;         cur = nxt; cA = nA; cB = nB; ++ui;
;         if constexpr (ALIGN_EPI) { if (wr == 1) PG8_BAR; }
;     DI void operator()(const pg8::f32x4 (&acc)[2][2][4][2], const pg8::Unit& u, int wr, int wc, int fr, int fq) const {
;     ...
; #pragma unroll
;         for (int ai = 0; ai < 2; ++ai)
; #pragma unroll
;             for (int m = 0; m < 4; ++m) {
;                 const int row = row0 + ai * 128 + m * 16; const float r = rs[ai][m];
;                 float hv[8];
; #pragma unroll
;                 for (int n = 0; n < 2; ++n) { const pg8::f32x4 g = acc[ai][0][m][n] * r, uu = acc[ai][1][m][n] * r;
; #pragma unroll
;                     for (int e = 0; e < 4; ++e) hv[4 * n + e] = g[e] * __frcp_rn(1.0f + __expf(-g[e])) * uu[e]; }
;                 u32x4 w; w.x = pk2(hv[0], hv[1]); w.y = pk2(hv[2], hv[3]); w.z = pk2(hv[4], hv[5]); w.w = pk2(hv[6], hv[7]);
;                 *(u32x4*)(H + (size_t)row * DFF + col0) = w;
;             }
	v_pk_mul_f32 v[44:45], v[44:45], v[48:49]
	v_pk_mul_f32 v[40:41], v[40:41], v[44:45]
	v_pk_mul_f32 v[44:45], v[46:47], v[142:143] op_sel_hi:[1,0]
	v_pk_mul_f32 v[46:47], v[44:45], v[240:241] op_sel_hi:[1,0]
	v_exp_f32_e32 v46, v46
	v_exp_f32_e32 v47, v47
	s_nop 0
	v_pk_add_f32 v[46:47], v[46:47], 1.0 op_sel_hi:[1,0]
	v_rcp_f32_e32 v47, v47
	v_rcp_f32_e32 v46, v46
	s_nop 0
	v_pk_mul_f32 v[44:45], v[44:45], v[46:47]
	v_pk_mul_f32 v[42:43], v[42:43], v[44:45]
	v_pk_mul_f32 v[44:45], v[36:37], v[240:241] op_sel_hi:[1,0]
	v_exp_f32_e32 v44, v44
	v_exp_f32_e32 v45, v45
	s_nop 0
	v_pk_add_f32 v[44:45], v[44:45], 1.0 op_sel_hi:[1,0]
	v_rcp_f32_e32 v45, v45
	v_rcp_f32_e32 v44, v44
	s_nop 0
	v_pk_mul_f32 v[36:37], v[36:37], v[44:45]
	v_pk_mul_f32 v[36:37], v[32:33], v[36:37]
	v_pk_mul_f32 v[32:33], v[38:39], v[142:143] op_sel_hi:[1,0]
	v_pk_mul_f32 v[38:39], v[32:33], v[240:241] op_sel_hi:[1,0]
	v_exp_f32_e32 v38, v38
	v_exp_f32_e32 v39, v39
	s_nop 0
	v_pk_add_f32 v[38:39], v[38:39], 1.0 op_sel_hi:[1,0]
	v_rcp_f32_e32 v39, v39
	v_rcp_f32_e32 v38, v38
	s_nop 0
	v_pk_mul_f32 v[32:33], v[32:33], v[38:39]
	v_add_u32_e32 v44, 0x90, v151
	v_pk_mul_f32 v[38:39], v[34:35], v[32:33]
	v_cvt_pk_bf16_f32 v34, v36, v37
	v_mad_i64_i32 v[36:37], s[16:17], v44, s9, v[112:113]
	v_cvt_pk_bf16_f32 v32, v40, v41
	v_cvt_pk_bf16_f32 v33, v42, v43
	v_cvt_pk_bf16_f32 v35, v38, v39
	v_lshl_add_u64 v[36:37], v[36:37], 0, v[114:115]
	global_store_dwordx4 v[36:37], v[32:35], off
	s_nop 1
	v_pk_mul_f32 v[32:33], v[28:29], v[240:241] op_sel_hi:[1,0]
	v_exp_f32_e32 v32, v32
	v_exp_f32_e32 v33, v33
	s_nop 0
	v_pk_add_f32 v[32:33], v[32:33], 1.0 op_sel_hi:[1,0]
	v_rcp_f32_e32 v33, v33
	v_rcp_f32_e32 v32, v32
	s_nop 0
	v_pk_mul_f32 v[28:29], v[28:29], v[32:33]
	v_pk_mul_f32 v[24:25], v[24:25], v[28:29]
	v_pk_mul_f32 v[28:29], v[30:31], v[140:141] op_sel_hi:[1,0]
	v_pk_mul_f32 v[30:31], v[28:29], v[240:241] op_sel_hi:[1,0]
	v_exp_f32_e32 v30, v30
	v_exp_f32_e32 v31, v31
	s_nop 0
	v_pk_add_f32 v[30:31], v[30:31], 1.0 op_sel_hi:[1,0]
	v_rcp_f32_e32 v31, v31
	v_rcp_f32_e32 v30, v30
	s_nop 0
	v_pk_mul_f32 v[28:29], v[28:29], v[30:31]
	v_pk_mul_f32 v[26:27], v[26:27], v[28:29]
	v_pk_mul_f32 v[28:29], v[20:21], v[240:241] op_sel_hi:[1,0]
	v_exp_f32_e32 v28, v28
	v_exp_f32_e32 v29, v29
	s_nop 0
	v_pk_add_f32 v[28:29], v[28:29], 1.0 op_sel_hi:[1,0]
	v_rcp_f32_e32 v29, v29
	v_rcp_f32_e32 v28, v28
	s_nop 0
	v_pk_mul_f32 v[20:21], v[20:21], v[28:29]
	v_pk_mul_f32 v[20:21], v[16:17], v[20:21]
	v_pk_mul_f32 v[16:17], v[22:23], v[140:141] op_sel_hi:[1,0]
	v_pk_mul_f32 v[22:23], v[16:17], v[240:241] op_sel_hi:[1,0]
	v_exp_f32_e32 v22, v22
	v_exp_f32_e32 v23, v23
	s_nop 0
	v_pk_add_f32 v[22:23], v[22:23], 1.0 op_sel_hi:[1,0]
	v_rcp_f32_e32 v23, v23
	v_rcp_f32_e32 v22, v22
	s_nop 0
	v_pk_mul_f32 v[16:17], v[16:17], v[22:23]
	v_add_u32_e32 v28, 0xa0, v151
	v_pk_mul_f32 v[22:23], v[18:19], v[16:17]
	v_cvt_pk_bf16_f32 v18, v20, v21
	v_mad_i64_i32 v[20:21], s[16:17], v28, s9, v[112:113]
	v_cvt_pk_bf16_f32 v16, v24, v25
	v_cvt_pk_bf16_f32 v17, v26, v27
	v_cvt_pk_bf16_f32 v19, v22, v23
	v_lshl_add_u64 v[20:21], v[20:21], 0, v[114:115]
	global_store_dwordx4 v[20:21], v[16:19], off
	s_nop 1
	v_pk_mul_f32 v[16:17], v[12:13], v[240:241] op_sel_hi:[1,0]
	v_exp_f32_e32 v16, v16
	v_exp_f32_e32 v17, v17
	s_nop 0
	v_pk_add_f32 v[16:17], v[16:17], 1.0 op_sel_hi:[1,0]
	v_rcp_f32_e32 v17, v17
	v_rcp_f32_e32 v16, v16
	s_nop 0
	v_pk_mul_f32 v[12:13], v[12:13], v[16:17]
	v_pk_mul_f32 v[8:9], v[8:9], v[12:13]
	v_pk_mul_f32 v[12:13], v[14:15], v[138:139] op_sel_hi:[1,0]
	v_pk_mul_f32 v[14:15], v[12:13], v[240:241] op_sel_hi:[1,0]
	v_exp_f32_e32 v14, v14
	v_exp_f32_e32 v15, v15
	s_nop 0
	v_pk_add_f32 v[14:15], v[14:15], 1.0 op_sel_hi:[1,0]
	v_rcp_f32_e32 v15, v15
	v_rcp_f32_e32 v14, v14
	s_nop 0
	v_pk_mul_f32 v[12:13], v[12:13], v[14:15]
	v_pk_mul_f32 v[10:11], v[10:11], v[12:13]
	v_pk_mul_f32 v[12:13], v[4:5], v[240:241] op_sel_hi:[1,0]
	v_exp_f32_e32 v12, v12
	v_exp_f32_e32 v13, v13
	s_nop 0
	v_pk_add_f32 v[12:13], v[12:13], 1.0 op_sel_hi:[1,0]
	v_rcp_f32_e32 v13, v13
	v_rcp_f32_e32 v12, v12
	s_nop 0
	v_pk_mul_f32 v[4:5], v[4:5], v[12:13]
	v_pk_mul_f32 v[4:5], v[0:1], v[4:5]
	v_pk_mul_f32 v[0:1], v[6:7], v[138:139] op_sel_hi:[1,0]
	v_pk_mul_f32 v[6:7], v[0:1], v[240:241] op_sel_hi:[1,0]
	v_exp_f32_e32 v6, v6
	v_exp_f32_e32 v7, v7
	s_nop 0
	v_pk_add_f32 v[6:7], v[6:7], 1.0 op_sel_hi:[1,0]
	v_rcp_f32_e32 v7, v7
	v_rcp_f32_e32 v6, v6
	s_nop 0
	v_pk_mul_f32 v[0:1], v[0:1], v[6:7]
	v_add_u32_e32 v12, 0xb0, v151
	v_pk_mul_f32 v[6:7], v[2:3], v[0:1]
	v_cvt_pk_bf16_f32 v2, v4, v5
	v_mad_i64_i32 v[4:5], s[16:17], v12, s9, v[112:113]
	v_cvt_pk_bf16_f32 v0, v8, v9
	v_cvt_pk_bf16_f32 v1, v10, v11
	v_cvt_pk_bf16_f32 v3, v6, v7
	v_lshl_add_u64 v[4:5], v[4:5], 0, v[114:115]
	s_mov_b64 s[16:17], -1
	s_andn2_b64 vcc, exec, s[40:41]
	global_store_dwordx4 v[4:5], v[0:3], off
	s_cbranch_vccnz .LBB0_509
	s_andn2_b64 vcc, exec, s[2:3]
	s_cbranch_vccnz .LBB0_508
	s_barrier
	s_branch .LBB0_508
